# mLSTM gates on wave 7 overlapped with chunk compute; post_scan: hyena transpose 9 tiles in flight per pass, row pass loads hoisted to one round trip per row
# speedup vs baseline: 1.0344x; 1.0031x over previous
; #define OPAQUE(x) asm volatile("" : "+v"(x))
; #define TIDX(p) ((p).wv * 64 + (int)__builtin_amdgcn_mbcnt_hi(~0u, __builtin_amdgcn_mbcnt_lo(~0u, 0u)))
; DI bfu* wsb(const PX& p, size_t off) { return (bfu*)(p.ws + off); }
; DI void post_scan(const PX& p, int l, int M, unsigned char* smem) {
;   {
;     bfu* tl = (bfu*)smem;
;     int tx = TIDX(p); OPAQUE(tx);
;     const bfu* Zt = wsb(p, OFF_BIG + B_ZHY);
;     bfu* Yh = wsb(p, OFF_BIG + B_YHY);
;     const int nt = (M >> 6) * 12;
;     for (int it = blockIdx.x; it < nt; it += gridDim.x) {
;       const int r0 = (it / 12) * 64, c0 = (it % 12) * 64;
;       __syncthreads();
; #pragma unroll
;       for (int i = 0; i < 2; i++) {
;         const int idx = tx + i * NTHR, ci = idx >> 4, t4 = (idx & 15) * 4;
;         const uint2 v = *(const uint2*)(Zt + (size_t)(c0 + ci) * NTOK + r0 + t4);
;         bfu* d = tl + ci * 66 + t4;
;         d[0] = (bfu)(v.x & 0xffffu); d[1] = (bfu)(v.x >> 16); d[2] = (bfu)(v.y & 0xffffu); d[3] = (bfu)(v.y >> 16);
;       }
;       __syncthreads();
; #pragma unroll
;       for (int i = 0; i < 2; i++) {
;         const int idx = tx + i * NTHR, ti = idx >> 4, c4 = (idx & 15) * 4;
;         const bfu* sp = tl + c4 * 66 + ti;
;         uint2 o;
;         o.x = (unsigned)sp[0] | ((unsigned)sp[66] << 16);
;         o.y = (unsigned)sp[132] | ((unsigned)sp[198] << 16);
;         *(uint2*)(Yh + (size_t)(r0 + ti) * 768 + c0 + c4) = o;
;       }
;     }
.LBB0_364:
	s_andn2_b64 vcc, exec, s[6:7]
	s_cbranch_vccnz .LBB0_420
	v_readlane_b32 s0, v255, 18
	s_mul_i32 s0, s0, 12
	v_readlane_b32 s1, v252, 0
	s_cmp_ge_i32 s1, s0
	s_waitcnt vmcnt(0) lgkmcnt(0)
	s_cbranch_scc1 .LBB0_368
	v_readlane_b32 s2, v253, 29
	v_readlane_b32 s3, v253, 30
	v_readlane_b32 s6, v254, 8
	v_readlane_b32 s7, v254, 9
	s_mul_i32 s8, s83, 9
	v_lshrrev_b32_e32 v2, 4, v188
	v_and_b32_e32 v3, 15, v188
	v_lshlrev_b32_e32 v4, 3, v3
	v_mov_b32_e32 v5, 0x12000
	v_mad_u32_u24 v10, v2, v5, v4
	v_add_u32_e32 v11, 0x240000, v10
	v_mov_b32_e32 v5, 0x84
	v_mad_u32_u24 v12, v2, v5, v4
	v_add_u32_e32 v13, 0x1080, v12
	v_lshlrev_b32_e32 v6, 1, v2
	v_mov_b32_e32 v5, 0x210
	v_mad_u32_u24 v14, v3, v5, v6
	v_mov_b32_e32 v5, 0x600
	v_mad_u32_u24 v15, v2, v5, v4
	v_add_u32_e32 v16, 0xc000, v15
	s_mov_b32 s19, s1
	s_cmp_lt_u32 s19, s0
	s_cselect_b32 s14, s19, s1
	s_mul_hi_u32 s15, s14, 0xaaaaaaab
	s_lshr_b32 s15, s15, 3
	s_mul_i32 s16, s15, 12
	s_sub_u32 s16, s14, s16
	s_mul_i32 s17, s16, 0x480000
	s_lshl_b32 s18, s15, 7
	s_add_u32 s17, s17, s18
	s_add_u32 s10, s2, s17
	s_addc_u32 s11, s3, 0
	global_load_dwordx2 v[20:21], v10, s[10:11]
	global_load_dwordx2 v[22:23], v11, s[10:11]
	s_add_u32 s19, s19, s83
	s_cmp_lt_u32 s19, s0
	s_cselect_b32 s14, s19, s1
	s_mul_hi_u32 s15, s14, 0xaaaaaaab
	s_lshr_b32 s15, s15, 3
	s_mul_i32 s16, s15, 12
	s_sub_u32 s16, s14, s16
	s_mul_i32 s17, s16, 0x480000
	s_lshl_b32 s18, s15, 7
	s_add_u32 s17, s17, s18
	s_add_u32 s10, s2, s17
	s_addc_u32 s11, s3, 0
	global_load_dwordx2 v[24:25], v10, s[10:11]
	global_load_dwordx2 v[26:27], v11, s[10:11]
	s_add_u32 s19, s19, s83
	s_cmp_lt_u32 s19, s0
	s_cselect_b32 s14, s19, s1
	s_mul_hi_u32 s15, s14, 0xaaaaaaab
	s_lshr_b32 s15, s15, 3
	s_mul_i32 s16, s15, 12
	s_sub_u32 s16, s14, s16
	s_mul_i32 s17, s16, 0x480000
	s_lshl_b32 s18, s15, 7
	s_add_u32 s17, s17, s18
	s_add_u32 s10, s2, s17
	s_addc_u32 s11, s3, 0
	global_load_dwordx2 v[28:29], v10, s[10:11]
	global_load_dwordx2 v[30:31], v11, s[10:11]
	s_add_u32 s19, s19, s83
	s_cmp_lt_u32 s19, s0
	s_cselect_b32 s14, s19, s1
	s_mul_hi_u32 s15, s14, 0xaaaaaaab
	s_lshr_b32 s15, s15, 3
	s_mul_i32 s16, s15, 12
	s_sub_u32 s16, s14, s16
	s_mul_i32 s17, s16, 0x480000
	s_lshl_b32 s18, s15, 7
	s_add_u32 s17, s17, s18
	s_add_u32 s10, s2, s17
	s_addc_u32 s11, s3, 0
	global_load_dwordx2 v[32:33], v10, s[10:11]
	global_load_dwordx2 v[34:35], v11, s[10:11]
	s_add_u32 s19, s19, s83
	s_cmp_lt_u32 s19, s0
	s_cselect_b32 s14, s19, s1
	s_mul_hi_u32 s15, s14, 0xaaaaaaab
	s_lshr_b32 s15, s15, 3
	s_mul_i32 s16, s15, 12
	s_sub_u32 s16, s14, s16
	s_mul_i32 s17, s16, 0x480000
	s_lshl_b32 s18, s15, 7
	s_add_u32 s17, s17, s18
	s_add_u32 s10, s2, s17
	s_addc_u32 s11, s3, 0
	global_load_dwordx2 v[36:37], v10, s[10:11]
	global_load_dwordx2 v[38:39], v11, s[10:11]
	s_add_u32 s19, s19, s83
	s_cmp_lt_u32 s19, s0
	s_cselect_b32 s14, s19, s1
	s_mul_hi_u32 s15, s14, 0xaaaaaaab
	s_lshr_b32 s15, s15, 3
	s_mul_i32 s16, s15, 12
	s_sub_u32 s16, s14, s16
	s_mul_i32 s17, s16, 0x480000
	s_lshl_b32 s18, s15, 7
	s_add_u32 s17, s17, s18
	s_add_u32 s10, s2, s17
	s_addc_u32 s11, s3, 0
	global_load_dwordx2 v[40:41], v10, s[10:11]
	global_load_dwordx2 v[42:43], v11, s[10:11]
	s_add_u32 s19, s19, s83
	s_cmp_lt_u32 s19, s0
	s_cselect_b32 s14, s19, s1
	s_mul_hi_u32 s15, s14, 0xaaaaaaab
	s_lshr_b32 s15, s15, 3
	s_mul_i32 s16, s15, 12
	s_sub_u32 s16, s14, s16
	s_mul_i32 s17, s16, 0x480000
	s_lshl_b32 s18, s15, 7
	s_add_u32 s17, s17, s18
	s_add_u32 s10, s2, s17
	s_addc_u32 s11, s3, 0
	global_load_dwordx2 v[44:45], v10, s[10:11]
	global_load_dwordx2 v[46:47], v11, s[10:11]
	s_add_u32 s19, s19, s83
	s_cmp_lt_u32 s19, s0
	s_cselect_b32 s14, s19, s1
	s_mul_hi_u32 s15, s14, 0xaaaaaaab
	s_lshr_b32 s15, s15, 3
	s_mul_i32 s16, s15, 12
	s_sub_u32 s16, s14, s16
	s_mul_i32 s17, s16, 0x480000
	s_lshl_b32 s18, s15, 7
	s_add_u32 s17, s17, s18
	s_add_u32 s10, s2, s17
	s_addc_u32 s11, s3, 0
	global_load_dwordx2 v[48:49], v10, s[10:11]
	global_load_dwordx2 v[50:51], v11, s[10:11]
	s_add_u32 s19, s19, s83
	s_cmp_lt_u32 s19, s0
	s_cselect_b32 s14, s19, s1
	s_mul_hi_u32 s15, s14, 0xaaaaaaab
	s_lshr_b32 s15, s15, 3
	s_mul_i32 s16, s15, 12
	s_sub_u32 s16, s14, s16
	s_mul_i32 s17, s16, 0x480000
	s_lshl_b32 s18, s15, 7
	s_add_u32 s17, s17, s18
	s_add_u32 s10, s2, s17
	s_addc_u32 s11, s3, 0
	global_load_dwordx2 v[52:53], v10, s[10:11]
	global_load_dwordx2 v[54:55], v11, s[10:11]
	s_waitcnt vmcnt(0)
; #define OPAQUE(x) asm volatile("" : "+v"(x))
; #define TIDX(p) ((p).wv * 64 + (int)__builtin_amdgcn_mbcnt_hi(~0u, __builtin_amdgcn_mbcnt_lo(~0u, 0u)))
; DI bfu* wsb(const PX& p, size_t off) { return (bfu*)(p.ws + off); }
; DI void post_scan(const PX& p, int l, int M, unsigned char* smem) {
;     ...
;     int tx = TIDX(p); OPAQUE(tx);
;     const bfu* Zt = wsb(p, OFF_BIG + B_ZHY);
;     bfu* Yh = wsb(p, OFF_BIG + B_YHY);
;     const int nt = (M >> 6) * 12;
;     for (int it = blockIdx.x; it < nt; it += gridDim.x) {
;       const int r0 = (it / 12) * 64, c0 = (it % 12) * 64;
;       __syncthreads();
; #pragma unroll
;       for (int i = 0; i < 2; i++) {
;         const int idx = tx + i * NTHR, ci = idx >> 4, t4 = (idx & 15) * 4;
;         const uint2 v = *(const uint2*)(Zt + (size_t)(c0 + ci) * NTOK + r0 + t4);
;         bfu* d = tl + ci * 66 + t4;
;         d[0] = (bfu)(v.x & 0xffffu); d[1] = (bfu)(v.x >> 16); d[2] = (bfu)(v.y & 0xffffu); d[3] = (bfu)(v.y >> 16);
;       }
;       __syncthreads();
.Lpt_loop:
	s_barrier
	s_waitcnt vmcnt(34)
	v_add_u32_e32 v17, 0x0, v12
	v_add_u32_e32 v18, 0x0, v13
	ds_write2_b32 v17, v20, v21 offset1:1
	ds_write2_b32 v18, v22, v23 offset1:1
	s_waitcnt vmcnt(32)
	v_add_u32_e32 v17, 0x2100, v12
	v_add_u32_e32 v18, 0x2100, v13
	ds_write2_b32 v17, v24, v25 offset1:1
	ds_write2_b32 v18, v26, v27 offset1:1
	s_waitcnt vmcnt(30)
	v_add_u32_e32 v17, 0x4200, v12
	v_add_u32_e32 v18, 0x4200, v13
	ds_write2_b32 v17, v28, v29 offset1:1
	ds_write2_b32 v18, v30, v31 offset1:1
	s_waitcnt vmcnt(28)
	v_add_u32_e32 v17, 0x6300, v12
	v_add_u32_e32 v18, 0x6300, v13
	ds_write2_b32 v17, v32, v33 offset1:1
	ds_write2_b32 v18, v34, v35 offset1:1
	s_waitcnt vmcnt(26)
	v_add_u32_e32 v17, 0x8400, v12
	v_add_u32_e32 v18, 0x8400, v13
	ds_write2_b32 v17, v36, v37 offset1:1
	ds_write2_b32 v18, v38, v39 offset1:1
	s_waitcnt vmcnt(24)
	v_add_u32_e32 v17, 0xa500, v12
	v_add_u32_e32 v18, 0xa500, v13
	ds_write2_b32 v17, v40, v41 offset1:1
	ds_write2_b32 v18, v42, v43 offset1:1
	s_waitcnt vmcnt(22)
	v_add_u32_e32 v17, 0xc600, v12
	v_add_u32_e32 v18, 0xc600, v13
	ds_write2_b32 v17, v44, v45 offset1:1
	ds_write2_b32 v18, v46, v47 offset1:1
	s_waitcnt vmcnt(20)
	v_add_u32_e32 v17, 0xe700, v12
	v_add_u32_e32 v18, 0xe700, v13
	ds_write2_b32 v17, v48, v49 offset1:1
	ds_write2_b32 v18, v50, v51 offset1:1
	s_waitcnt vmcnt(18)
	v_add_u32_e32 v17, 0x10800, v12
	v_add_u32_e32 v18, 0x10800, v13
	ds_write2_b32 v17, v52, v53 offset1:1
	ds_write2_b32 v18, v54, v55 offset1:1
	s_waitcnt lgkmcnt(0)
	s_add_u32 s9, s1, s8
	s_cmp_ge_u32 s9, s0
	s_cbranch_scc1 .Lpt_nonext
	s_mov_b32 s19, s9
	s_cmp_lt_u32 s19, s0
	s_cselect_b32 s14, s19, s9
	s_mul_hi_u32 s15, s14, 0xaaaaaaab
	s_lshr_b32 s15, s15, 3
	s_mul_i32 s16, s15, 12
	s_sub_u32 s16, s14, s16
	s_mul_i32 s17, s16, 0x480000
	s_lshl_b32 s18, s15, 7
	s_add_u32 s17, s17, s18
	s_add_u32 s10, s2, s17
	s_addc_u32 s11, s3, 0
	global_load_dwordx2 v[20:21], v10, s[10:11]
	global_load_dwordx2 v[22:23], v11, s[10:11]
	s_add_u32 s19, s19, s83
	s_cmp_lt_u32 s19, s0
	s_cselect_b32 s14, s19, s9
	s_mul_hi_u32 s15, s14, 0xaaaaaaab
	s_lshr_b32 s15, s15, 3
	s_mul_i32 s16, s15, 12
	s_sub_u32 s16, s14, s16
	s_mul_i32 s17, s16, 0x480000
	s_lshl_b32 s18, s15, 7
	s_add_u32 s17, s17, s18
	s_add_u32 s10, s2, s17
	s_addc_u32 s11, s3, 0
	global_load_dwordx2 v[24:25], v10, s[10:11]
	global_load_dwordx2 v[26:27], v11, s[10:11]
	s_add_u32 s19, s19, s83
	s_cmp_lt_u32 s19, s0
	s_cselect_b32 s14, s19, s9
	s_mul_hi_u32 s15, s14, 0xaaaaaaab
	s_lshr_b32 s15, s15, 3
	s_mul_i32 s16, s15, 12
	s_sub_u32 s16, s14, s16
	s_mul_i32 s17, s16, 0x480000
	s_lshl_b32 s18, s15, 7
	s_add_u32 s17, s17, s18
	s_add_u32 s10, s2, s17
	s_addc_u32 s11, s3, 0
	global_load_dwordx2 v[28:29], v10, s[10:11]
	global_load_dwordx2 v[30:31], v11, s[10:11]
	s_add_u32 s19, s19, s83
	s_cmp_lt_u32 s19, s0
	s_cselect_b32 s14, s19, s9
	s_mul_hi_u32 s15, s14, 0xaaaaaaab
	s_lshr_b32 s15, s15, 3
	s_mul_i32 s16, s15, 12
	s_sub_u32 s16, s14, s16
	s_mul_i32 s17, s16, 0x480000
	s_lshl_b32 s18, s15, 7
	s_add_u32 s17, s17, s18
	s_add_u32 s10, s2, s17
	s_addc_u32 s11, s3, 0
	global_load_dwordx2 v[32:33], v10, s[10:11]
	global_load_dwordx2 v[34:35], v11, s[10:11]
	s_add_u32 s19, s19, s83
	s_cmp_lt_u32 s19, s0
	s_cselect_b32 s14, s19, s9
	s_mul_hi_u32 s15, s14, 0xaaaaaaab
	s_lshr_b32 s15, s15, 3
	s_mul_i32 s16, s15, 12
	s_sub_u32 s16, s14, s16
	s_mul_i32 s17, s16, 0x480000
	s_lshl_b32 s18, s15, 7
	s_add_u32 s17, s17, s18
	s_add_u32 s10, s2, s17
	s_addc_u32 s11, s3, 0
	global_load_dwordx2 v[36:37], v10, s[10:11]
	global_load_dwordx2 v[38:39], v11, s[10:11]
	s_add_u32 s19, s19, s83
	s_cmp_lt_u32 s19, s0
	s_cselect_b32 s14, s19, s9
	s_mul_hi_u32 s15, s14, 0xaaaaaaab
	s_lshr_b32 s15, s15, 3
	s_mul_i32 s16, s15, 12
	s_sub_u32 s16, s14, s16
	s_mul_i32 s17, s16, 0x480000
	s_lshl_b32 s18, s15, 7
	s_add_u32 s17, s17, s18
	s_add_u32 s10, s2, s17
	s_addc_u32 s11, s3, 0
	global_load_dwordx2 v[40:41], v10, s[10:11]
	global_load_dwordx2 v[42:43], v11, s[10:11]
	s_add_u32 s19, s19, s83
	s_cmp_lt_u32 s19, s0
	s_cselect_b32 s14, s19, s9
	s_mul_hi_u32 s15, s14, 0xaaaaaaab
	s_lshr_b32 s15, s15, 3
	s_mul_i32 s16, s15, 12
	s_sub_u32 s16, s14, s16
	s_mul_i32 s17, s16, 0x480000
	s_lshl_b32 s18, s15, 7
	s_add_u32 s17, s17, s18
	s_add_u32 s10, s2, s17
	s_addc_u32 s11, s3, 0
	global_load_dwordx2 v[44:45], v10, s[10:11]
	global_load_dwordx2 v[46:47], v11, s[10:11]
	s_add_u32 s19, s19, s83
	s_cmp_lt_u32 s19, s0
	s_cselect_b32 s14, s19, s9
	s_mul_hi_u32 s15, s14, 0xaaaaaaab
	s_lshr_b32 s15, s15, 3
	s_mul_i32 s16, s15, 12
	s_sub_u32 s16, s14, s16
	s_mul_i32 s17, s16, 0x480000
	s_lshl_b32 s18, s15, 7
	s_add_u32 s17, s17, s18
	s_add_u32 s10, s2, s17
	s_addc_u32 s11, s3, 0
	global_load_dwordx2 v[48:49], v10, s[10:11]
	global_load_dwordx2 v[50:51], v11, s[10:11]
	s_add_u32 s19, s19, s83
	s_cmp_lt_u32 s19, s0
	s_cselect_b32 s14, s19, s9
	s_mul_hi_u32 s15, s14, 0xaaaaaaab
	s_lshr_b32 s15, s15, 3
	s_mul_i32 s16, s15, 12
	s_sub_u32 s16, s14, s16
	s_mul_i32 s17, s16, 0x480000
	s_lshl_b32 s18, s15, 7
	s_add_u32 s17, s17, s18
	s_add_u32 s10, s2, s17
	s_addc_u32 s11, s3, 0
	global_load_dwordx2 v[52:53], v10, s[10:11]
	global_load_dwordx2 v[54:55], v11, s[10:11]
; DI void post_scan(const PX& p, int l, int M, unsigned char* smem) {
;     ...
; #pragma unroll
;       for (int i = 0; i < 2; i++) {
;         const int idx = tx + i * NTHR, ti = idx >> 4, c4 = (idx & 15) * 4;
;         const bfu* sp = tl + c4 * 66 + ti;
;         uint2 o;
;         o.x = (unsigned)sp[0] | ((unsigned)sp[66] << 16);
;         o.y = (unsigned)sp[132] | ((unsigned)sp[198] << 16);
;         *(uint2*)(Yh + (size_t)(r0 + ti) * 768 + c0 + c4) = o;
;       }
.Lpt_nonext:
	s_barrier
	v_add_u32_e32 v19, 0x0, v14
	ds_read_u16 v96, v19 offset:0
	ds_read_u16 v97, v19 offset:132
	ds_read_u16 v98, v19 offset:264
	ds_read_u16 v99, v19 offset:396
	ds_read_u16 v100, v19 offset:64
	ds_read_u16 v101, v19 offset:196
	ds_read_u16 v102, v19 offset:328
	ds_read_u16 v103, v19 offset:460
	s_mov_b32 s19, s1
	s_cmp_lt_u32 s19, s0
	s_cselect_b32 s14, s19, s1
	s_mul_hi_u32 s15, s14, 0xaaaaaaab
	s_lshr_b32 s15, s15, 3
	s_mul_i32 s16, s15, 12
	s_sub_u32 s16, s14, s16
	s_mul_i32 s17, s15, 0x18000
	s_lshl_b32 s18, s16, 7
	s_add_u32 s17, s17, s18
	s_add_u32 s12, s6, s17
	s_addc_u32 s13, s7, 0
	v_add_u32_e32 v9, 0x2100, v14
	ds_read_u16 v104, v9 offset:0
	ds_read_u16 v105, v9 offset:132
	ds_read_u16 v106, v9 offset:264
	ds_read_u16 v107, v9 offset:396
	ds_read_u16 v108, v9 offset:64
	ds_read_u16 v109, v9 offset:196
	ds_read_u16 v110, v9 offset:328
	ds_read_u16 v111, v9 offset:460
	s_waitcnt lgkmcnt(8)
	v_lshl_or_b32 v60, v97, 16, v96
	v_lshl_or_b32 v61, v99, 16, v98
	v_lshl_or_b32 v62, v101, 16, v100
	v_lshl_or_b32 v63, v103, 16, v102
	global_store_dwordx2 v15, v[60:61], s[12:13]
	global_store_dwordx2 v16, v[62:63], s[12:13]
	s_add_u32 s19, s19, s83
	s_cmp_lt_u32 s19, s0
	s_cselect_b32 s14, s19, s1
	s_mul_hi_u32 s15, s14, 0xaaaaaaab
	s_lshr_b32 s15, s15, 3
	s_mul_i32 s16, s15, 12
	s_sub_u32 s16, s14, s16
	s_mul_i32 s17, s15, 0x18000
	s_lshl_b32 s18, s16, 7
	s_add_u32 s17, s17, s18
	s_add_u32 s12, s6, s17
	s_addc_u32 s13, s7, 0
	v_add_u32_e32 v19, 0x4200, v14
	ds_read_u16 v96, v19 offset:0
	ds_read_u16 v97, v19 offset:132
	ds_read_u16 v98, v19 offset:264
	ds_read_u16 v99, v19 offset:396
	ds_read_u16 v100, v19 offset:64
	ds_read_u16 v101, v19 offset:196
	ds_read_u16 v102, v19 offset:328
	ds_read_u16 v103, v19 offset:460
	s_waitcnt lgkmcnt(8)
	v_lshl_or_b32 v64, v105, 16, v104
	v_lshl_or_b32 v65, v107, 16, v106
	v_lshl_or_b32 v66, v109, 16, v108
	v_lshl_or_b32 v67, v111, 16, v110
	global_store_dwordx2 v15, v[64:65], s[12:13]
	global_store_dwordx2 v16, v[66:67], s[12:13]
	s_add_u32 s19, s19, s83
	s_cmp_lt_u32 s19, s0
	s_cselect_b32 s14, s19, s1
	s_mul_hi_u32 s15, s14, 0xaaaaaaab
	s_lshr_b32 s15, s15, 3
	s_mul_i32 s16, s15, 12
	s_sub_u32 s16, s14, s16
	s_mul_i32 s17, s15, 0x18000
	s_lshl_b32 s18, s16, 7
	s_add_u32 s17, s17, s18
	s_add_u32 s12, s6, s17
	s_addc_u32 s13, s7, 0
	v_add_u32_e32 v9, 0x6300, v14
	ds_read_u16 v104, v9 offset:0
	ds_read_u16 v105, v9 offset:132
	ds_read_u16 v106, v9 offset:264
	ds_read_u16 v107, v9 offset:396
	ds_read_u16 v108, v9 offset:64
	ds_read_u16 v109, v9 offset:196
	ds_read_u16 v110, v9 offset:328
	ds_read_u16 v111, v9 offset:460
	s_waitcnt lgkmcnt(8)
	v_lshl_or_b32 v68, v97, 16, v96
	v_lshl_or_b32 v69, v99, 16, v98
	v_lshl_or_b32 v70, v101, 16, v100
	v_lshl_or_b32 v71, v103, 16, v102
	global_store_dwordx2 v15, v[68:69], s[12:13]
	global_store_dwordx2 v16, v[70:71], s[12:13]
	s_add_u32 s19, s19, s83
	s_cmp_lt_u32 s19, s0
	s_cselect_b32 s14, s19, s1
	s_mul_hi_u32 s15, s14, 0xaaaaaaab
	s_lshr_b32 s15, s15, 3
	s_mul_i32 s16, s15, 12
	s_sub_u32 s16, s14, s16
	s_mul_i32 s17, s15, 0x18000
	s_lshl_b32 s18, s16, 7
	s_add_u32 s17, s17, s18
	s_add_u32 s12, s6, s17
	s_addc_u32 s13, s7, 0
	v_add_u32_e32 v19, 0x8400, v14
	ds_read_u16 v96, v19 offset:0
	ds_read_u16 v97, v19 offset:132
	ds_read_u16 v98, v19 offset:264
	ds_read_u16 v99, v19 offset:396
	ds_read_u16 v100, v19 offset:64
	ds_read_u16 v101, v19 offset:196
	ds_read_u16 v102, v19 offset:328
	ds_read_u16 v103, v19 offset:460
	s_waitcnt lgkmcnt(8)
; DI void post_scan(const PX& p, int l, int M, unsigned char* smem) {
;     ...
;     for (int it = blockIdx.x; it < nt; it += gridDim.x) {
;     ...
; #pragma unroll
;       for (int i = 0; i < 2; i++) {
;         const int idx = tx + i * NTHR, ti = idx >> 4, c4 = (idx & 15) * 4;
;         const bfu* sp = tl + c4 * 66 + ti;
;         uint2 o;
;         o.x = (unsigned)sp[0] | ((unsigned)sp[66] << 16);
;         o.y = (unsigned)sp[132] | ((unsigned)sp[198] << 16);
;         *(uint2*)(Yh + (size_t)(r0 + ti) * 768 + c0 + c4) = o;
;       }
	v_lshl_or_b32 v72, v105, 16, v104
	v_lshl_or_b32 v73, v107, 16, v106
	v_lshl_or_b32 v74, v109, 16, v108
	v_lshl_or_b32 v75, v111, 16, v110
	global_store_dwordx2 v15, v[72:73], s[12:13]
	global_store_dwordx2 v16, v[74:75], s[12:13]
	s_add_u32 s19, s19, s83
	s_cmp_lt_u32 s19, s0
	s_cselect_b32 s14, s19, s1
	s_mul_hi_u32 s15, s14, 0xaaaaaaab
	s_lshr_b32 s15, s15, 3
	s_mul_i32 s16, s15, 12
	s_sub_u32 s16, s14, s16
	s_mul_i32 s17, s15, 0x18000
	s_lshl_b32 s18, s16, 7
	s_add_u32 s17, s17, s18
	s_add_u32 s12, s6, s17
	s_addc_u32 s13, s7, 0
	v_add_u32_e32 v9, 0xa500, v14
	ds_read_u16 v104, v9 offset:0
	ds_read_u16 v105, v9 offset:132
	ds_read_u16 v106, v9 offset:264
	ds_read_u16 v107, v9 offset:396
	ds_read_u16 v108, v9 offset:64
	ds_read_u16 v109, v9 offset:196
	ds_read_u16 v110, v9 offset:328
	ds_read_u16 v111, v9 offset:460
	s_waitcnt lgkmcnt(8)
	v_lshl_or_b32 v76, v97, 16, v96
	v_lshl_or_b32 v77, v99, 16, v98
	v_lshl_or_b32 v78, v101, 16, v100
	v_lshl_or_b32 v79, v103, 16, v102
	global_store_dwordx2 v15, v[76:77], s[12:13]
	global_store_dwordx2 v16, v[78:79], s[12:13]
	s_add_u32 s19, s19, s83
	s_cmp_lt_u32 s19, s0
	s_cselect_b32 s14, s19, s1
	s_mul_hi_u32 s15, s14, 0xaaaaaaab
	s_lshr_b32 s15, s15, 3
	s_mul_i32 s16, s15, 12
	s_sub_u32 s16, s14, s16
	s_mul_i32 s17, s15, 0x18000
	s_lshl_b32 s18, s16, 7
	s_add_u32 s17, s17, s18
	s_add_u32 s12, s6, s17
	s_addc_u32 s13, s7, 0
	v_add_u32_e32 v19, 0xc600, v14
	ds_read_u16 v96, v19 offset:0
	ds_read_u16 v97, v19 offset:132
	ds_read_u16 v98, v19 offset:264
	ds_read_u16 v99, v19 offset:396
	ds_read_u16 v100, v19 offset:64
	ds_read_u16 v101, v19 offset:196
	ds_read_u16 v102, v19 offset:328
	ds_read_u16 v103, v19 offset:460
	s_waitcnt lgkmcnt(8)
	v_lshl_or_b32 v80, v105, 16, v104
	v_lshl_or_b32 v81, v107, 16, v106
	v_lshl_or_b32 v82, v109, 16, v108
	v_lshl_or_b32 v83, v111, 16, v110
	global_store_dwordx2 v15, v[80:81], s[12:13]
	global_store_dwordx2 v16, v[82:83], s[12:13]
	s_add_u32 s19, s19, s83
	s_cmp_lt_u32 s19, s0
	s_cselect_b32 s14, s19, s1
	s_mul_hi_u32 s15, s14, 0xaaaaaaab
	s_lshr_b32 s15, s15, 3
	s_mul_i32 s16, s15, 12
	s_sub_u32 s16, s14, s16
	s_mul_i32 s17, s15, 0x18000
	s_lshl_b32 s18, s16, 7
	s_add_u32 s17, s17, s18
	s_add_u32 s12, s6, s17
	s_addc_u32 s13, s7, 0
	v_add_u32_e32 v9, 0xe700, v14
	ds_read_u16 v104, v9 offset:0
	ds_read_u16 v105, v9 offset:132
	ds_read_u16 v106, v9 offset:264
	ds_read_u16 v107, v9 offset:396
	ds_read_u16 v108, v9 offset:64
	ds_read_u16 v109, v9 offset:196
	ds_read_u16 v110, v9 offset:328
	ds_read_u16 v111, v9 offset:460
	s_waitcnt lgkmcnt(8)
	v_lshl_or_b32 v84, v97, 16, v96
	v_lshl_or_b32 v85, v99, 16, v98
	v_lshl_or_b32 v86, v101, 16, v100
	v_lshl_or_b32 v87, v103, 16, v102
	global_store_dwordx2 v15, v[84:85], s[12:13]
	global_store_dwordx2 v16, v[86:87], s[12:13]
	s_add_u32 s19, s19, s83
	s_cmp_lt_u32 s19, s0
	s_cselect_b32 s14, s19, s1
	s_mul_hi_u32 s15, s14, 0xaaaaaaab
	s_lshr_b32 s15, s15, 3
	s_mul_i32 s16, s15, 12
	s_sub_u32 s16, s14, s16
	s_mul_i32 s17, s15, 0x18000
	s_lshl_b32 s18, s16, 7
	s_add_u32 s17, s17, s18
	s_add_u32 s12, s6, s17
	s_addc_u32 s13, s7, 0
	v_add_u32_e32 v19, 0x10800, v14
	ds_read_u16 v96, v19 offset:0
	ds_read_u16 v97, v19 offset:132
	ds_read_u16 v98, v19 offset:264
	ds_read_u16 v99, v19 offset:396
	ds_read_u16 v100, v19 offset:64
	ds_read_u16 v101, v19 offset:196
	ds_read_u16 v102, v19 offset:328
	ds_read_u16 v103, v19 offset:460
	s_waitcnt lgkmcnt(8)
	v_lshl_or_b32 v88, v105, 16, v104
	v_lshl_or_b32 v89, v107, 16, v106
	v_lshl_or_b32 v90, v109, 16, v108
	v_lshl_or_b32 v91, v111, 16, v110
	global_store_dwordx2 v15, v[88:89], s[12:13]
	global_store_dwordx2 v16, v[90:91], s[12:13]
	s_add_u32 s19, s19, s83
	s_cmp_lt_u32 s19, s0
	s_cselect_b32 s14, s19, s1
	s_mul_hi_u32 s15, s14, 0xaaaaaaab
	s_lshr_b32 s15, s15, 3
	s_mul_i32 s16, s15, 12
	s_sub_u32 s16, s14, s16
	s_mul_i32 s17, s15, 0x18000
	s_lshl_b32 s18, s16, 7
	s_add_u32 s17, s17, s18
	s_add_u32 s12, s6, s17
	s_addc_u32 s13, s7, 0
	s_waitcnt lgkmcnt(0)
	v_lshl_or_b32 v92, v97, 16, v96
	v_lshl_or_b32 v93, v99, 16, v98
	v_lshl_or_b32 v94, v101, 16, v100
	v_lshl_or_b32 v95, v103, 16, v102
	global_store_dwordx2 v15, v[92:93], s[12:13]
	global_store_dwordx2 v16, v[94:95], s[12:13]
	s_mov_b32 s1, s9
	s_cmp_lt_u32 s1, s0
	s_cbranch_scc1 .Lpt_loop

; DI unsigned pack2(float a, float b) { f32x2_t v = {a, b}; bf16x2_t r = __builtin_convertvector(v, bf16x2_t); return __builtin_bit_cast(unsigned, r); }
; DI float lo16(unsigned u) { return __uint_as_float(u << 16); }
; DI float hi16(unsigned u) { return __uint_as_float(u & 0xffff0000u); }
; DI float sigmoidf_(float x) { return 1.f / (1.f + __expf(-x)); }
; DI void post_scan(const PX& p, int l, int M, unsigned char* smem) {
;     ...
;   for (int r = wg; r < M; r += nw) {
;     const size_t ro = (size_t)r * 768 + lane * 12;
;     {
;       float x[12];
;       const uint2* hf = (const uint2*)(Hf + ro);
;       const uint2* hb = (const uint2*)(Hb + ro);
;       float s = 0.f;
; #pragma unroll
;       for (int i = 0; i < 3; i++) {
;         const uint2 a = hf[i], bq = hb[i];
;         x[4 * i] = lo16(a.x) + lo16(bq.x); x[4 * i + 1] = hi16(a.x) + hi16(bq.x);
;         x[4 * i + 2] = lo16(a.y) + lo16(bq.y); x[4 * i + 3] = hi16(a.y) + hi16(bq.y);
;         s += x[4 * i] + x[4 * i + 1] + x[4 * i + 2] + x[4 * i + 3];
;       }
; #pragma unroll
;       for (int o = 8; o >= 1; o >>= 1) s += __shfl_xor(s, o);
;       const float mu = s * (1.f / 192.f);
;       float q = 0.f;
; #pragma unroll
;       for (int i = 0; i < 12; i++) { x[i] -= mu; q += x[i] * x[i]; }
; #pragma unroll
;       for (int o = 8; o >= 1; o >>= 1) q += __shfl_xor(q, o);
;       const float rs = rsqrtf(q * (1.f / 192.f) + 1e-5f);
;       const uint2* og = (const uint2*)(Zml + (size_t)r * 3072 + 2304 + lane * 12);
;       const float4* gg = (const float4*)(ng + lane * 12);
; #pragma unroll
;       for (int i = 0; i < 3; i++) {
;         const uint2 o = og[i];
;         const float4 g4 = ngv[i];
;         uint2 w_;
;         w_.x = pack2(x[4 * i] * rs * g4.x * sigmoidf_(lo16(o.x)), x[4 * i + 1] * rs * g4.y * sigmoidf_(hi16(o.x)));
;         w_.y = pack2(x[4 * i + 2] * rs * g4.z * sigmoidf_(lo16(o.y)), x[4 * i + 3] * rs * g4.w * sigmoidf_(hi16(o.y)));
;         ((uint2*)(Hf + ro))[i] = w_;
;       }
;     }
;     {
;       const uint2* yf = (const uint2*)(Yf + ro);
;       const uint2* yb = (const uint2*)(Yb + ro);
;       const uint2* zu = (const uint2*)(Zu + ro);
;       const float4* dd = (const float4*)(sd + lane * 12);
; #pragma unroll
;       for (int i = 0; i < 3; i++) {
;         const uint2 a = yf[i], bq = yb[i], u = zu[i];
.LBB0_371:
	v_lshl_add_u64 v[30:31], v[28:29], 0, v[0:1]
	s_mov_b64 s[2:3], 0x2f618100
	v_add_co_u32_e32 v32, vcc, 0x2f618000, v30
	v_lshl_add_u64 v[34:35], v[30:31], 0, s[2:3]
	s_nop 0
	v_addc_co_u32_e32 v33, vcc, 0, v31, vcc
	global_load_dwordx4 v[46:49], v[32:33], off offset:256
	global_load_dwordx2 v[58:59], v[34:35], off offset:16
	v_add_co_u32_e32 v34, vcc, 0x32c18000, v30
	s_mov_b64 s[2:3], 0x32c18100
	s_nop 0
	v_addc_co_u32_e32 v35, vcc, 0, v31, vcc
	v_lshl_add_u64 v[36:37], v[30:31], 0, s[2:3]
	global_load_dwordx4 v[54:57], v[34:35], off offset:256
	global_load_dwordx2 v[60:61], v[36:37], off offset:16
	v_lshl_add_u64 v[34:35], v[26:27], 0, v[0:1]
	s_mov_b32 s1, 0x1afd9000
	v_add_co_u32_e32 v34, vcc, s1, v34
	s_mov_b32 s1, 0x800000
	s_nop 0
	v_addc_co_u32_e32 v35, vcc, 0, v35, vcc
	global_load_dwordx2 v[50:51], v[34:35], off offset:768
	global_load_dwordx2 v[100:101], v[34:35], off offset:776
	global_load_dwordx2 v[102:103], v[34:35], off offset:784
	v_add_co_u32_e32 v122, vcc, 0x36218000, v30
	s_nop 1
	v_addc_co_u32_e32 v123, vcc, 0, v31, vcc
	v_add_co_u32_e32 v124, vcc, 0x39818000, v30
	s_nop 1
	v_addc_co_u32_e32 v125, vcc, 0, v31, vcc
	v_add_co_u32_e32 v126, vcc, 0x28a18000, v30
	s_nop 1
	v_addc_co_u32_e32 v127, vcc, 0, v31, vcc
	global_load_dwordx2 v[104:105], v[122:123], off offset:256
	global_load_dwordx2 v[106:107], v[124:125], off offset:256
	global_load_dwordx2 v[108:109], v[126:127], off offset:256
	global_load_dwordx2 v[110:111], v[122:123], off offset:264
	global_load_dwordx2 v[112:113], v[124:125], off offset:264
	global_load_dwordx2 v[114:115], v[126:127], off offset:264
	global_load_dwordx2 v[116:117], v[122:123], off offset:272
	global_load_dwordx2 v[118:119], v[124:125], off offset:272
	global_load_dwordx2 v[120:121], v[126:127], off offset:272
	s_waitcnt vmcnt(15)
	v_lshlrev_b32_e32 v36, 16, v46
	v_and_b32_e32 v37, 0xffff0000, v46
	v_lshlrev_b32_e32 v38, 16, v47
	v_and_b32_e32 v39, 0xffff0000, v47
	v_lshlrev_b32_e32 v46, 16, v48
	v_and_b32_e32 v47, 0xffff0000, v48
	s_waitcnt vmcnt(13)
	v_lshlrev_b32_e32 v40, 16, v54
	v_and_b32_e32 v41, 0xffff0000, v54
	v_pk_add_f32 v[40:41], v[36:37], v[40:41]
	v_lshlrev_b32_e32 v42, 16, v55
	v_and_b32_e32 v43, 0xffff0000, v55
	v_pk_add_f32 v[38:39], v[38:39], v[42:43]
	v_pk_add_f32 v[42:43], v[40:41], v[40:41] op_sel:[0,1] op_sel_hi:[1,0]
	v_lshlrev_b32_e32 v44, 16, v56
	v_pk_add_f32 v[68:69], v[38:39], v[42:43]
	s_waitcnt vmcnt(11)
	v_lshlrev_b32_e32 v48, 16, v50
	v_mul_f32_e32 v48, 0xbfb8aa3b, v48
	v_exp_f32_e32 v52, v48
	v_and_b32_e32 v48, 0xffff0000, v50
	v_mul_f32_e32 v48, 0xbfb8aa3b, v48
	v_exp_f32_e32 v53, v48
	v_lshlrev_b32_e32 v48, 16, v51
	v_mul_f32_e32 v48, 0xbfb8aa3b, v48
	v_exp_f32_e32 v54, v48
	v_and_b32_e32 v48, 0xffff0000, v51
	v_mul_f32_e32 v48, 0xbfb8aa3b, v48
	v_pk_add_f32 v[36:37], v[52:53], 1.0 op_sel_hi:[1,0]
	v_exp_f32_e32 v55, v48
	v_div_scale_f32 v48, s[2:3], v37, v37, 1.0
	v_rcp_f32_e32 v50, v48
	v_lshlrev_b32_e32 v42, 16, v49
	v_lshlrev_b32_e32 v43, 16, v58
	v_pk_add_f32 v[54:55], v[54:55], 1.0 op_sel_hi:[1,0]
	v_fma_f32 v51, -v48, v50, 1.0
	v_fmac_f32_e32 v50, v51, v50
	v_div_scale_f32 v51, vcc, 1.0, v37, 1.0
	v_mul_f32_e32 v52, v51, v50
	v_fma_f32 v53, -v48, v52, v51
	v_fmac_f32_e32 v52, v53, v50
	v_fma_f32 v48, -v48, v52, v51
	v_div_fmas_f32 v48, v48, v50, v52
	v_div_fixup_f32 v37, v48, v37, 1.0
	v_div_scale_f32 v48, s[2:3], v36, v36, 1.0
	v_rcp_f32_e32 v50, v48
	v_and_b32_e32 v45, 0xffff0000, v56
	v_and_b32_e32 v56, 0xffff0000, v57
	v_pk_add_f32 v[44:45], v[46:47], v[44:45]
	v_fma_f32 v51, -v48, v50, 1.0
	v_fmac_f32_e32 v50, v51, v50
	v_div_scale_f32 v51, vcc, 1.0, v36, 1.0
	v_mul_f32_e32 v52, v51, v50
	v_fma_f32 v53, -v48, v52, v51
	v_fmac_f32_e32 v52, v53, v50
	v_fma_f32 v48, -v48, v52, v51
	v_div_fmas_f32 v48, v48, v50, v52
	v_lshlrev_b32_e32 v50, 16, v57
	v_lshlrev_b32_e32 v51, 16, v60
	v_div_fixup_f32 v36, v48, v36, 1.0
	v_pk_add_f32 v[42:43], v[42:43], v[50:51]
	v_and_b32_e32 v51, 0xffff0000, v58
	v_and_b32_e32 v48, 0xffff0000, v49
	v_lshlrev_b32_e32 v49, 16, v59
	v_and_b32_e32 v50, 0xffff0000, v59
	v_pk_add_f32 v[58:59], v[38:39], v[68:69] op_sel:[1,0] op_sel_hi:[0,1]
	v_mov_b32_e32 v59, v50
	v_div_scale_f32 v50, s[2:3], v55, v55, 1.0
	v_rcp_f32_e32 v52, v50
	v_lshlrev_b32_e32 v57, 16, v61
	v_pk_add_f32 v[48:49], v[48:49], v[56:57]
	v_and_b32_e32 v57, 0xffff0000, v61
	v_mov_b32_e32 v56, v1
	v_and_b32_e32 v53, 0xffff0000, v60
	v_pk_add_f32 v[60:61], v[58:59], v[56:57]
	v_fma_f32 v58, -v50, v52, 1.0
	v_fmac_f32_e32 v52, v58, v52
	v_div_scale_f32 v58, vcc, 1.0, v55, 1.0
	v_mul_f32_e32 v59, v58, v52
	v_fma_f32 v67, -v50, v59, v58
	v_fmac_f32_e32 v59, v67, v52
	v_fma_f32 v50, -v50, v59, v58
	v_div_fmas_f32 v50, v50, v52, v59
	v_div_fixup_f32 v55, v50, v55, 1.0
	v_div_scale_f32 v50, s[2:3], v54, v54, 1.0
	v_rcp_f32_e32 v52, v50
	v_mov_b32_e32 v57, v49
	v_mov_b32_e32 v56, v61
	v_fma_f32 v58, -v50, v52, 1.0
	v_fmac_f32_e32 v52, v58, v52
	v_div_scale_f32 v58, vcc, 1.0, v54, 1.0
	v_mul_f32_e32 v59, v58, v52
	v_fma_f32 v67, -v50, v59, v58
	v_fmac_f32_e32 v59, v67, v52
	v_fma_f32 v50, -v50, v59, v58
	v_div_fmas_f32 v50, v50, v52, v59
	v_div_fixup_f32 v54, v50, v54, 1.0
	v_mov_b32_e32 v50, v44
	v_mov_b32_e32 v52, v45
	v_pk_add_f32 v[46:47], v[50:51], v[52:53]
	v_mov_b32_e32 v59, v48
	v_pk_add_f32 v[50:51], v[42:43], v[46:47]
	v_mov_b32_e32 v58, v42
	v_pk_add_f32 v[48:49], v[48:49], v[50:51]
	s_nop 0
	v_pk_add_f32 v[48:49], v[60:61], v[48:49]
	s_nop 0
	v_add_f32_e32 v42, v48, v49
	ds_bpermute_b32 v46, v63, v42
	s_waitcnt lgkmcnt(0)
	v_add_f32_e32 v42, v42, v46
	ds_bpermute_b32 v46, v64, v42
	s_waitcnt lgkmcnt(0)
; DI unsigned pack2(float a, float b) { f32x2_t v = {a, b}; bf16x2_t r = __builtin_convertvector(v, bf16x2_t); return __builtin_bit_cast(unsigned, r); }
; DI float lo16(unsigned u) { return __uint_as_float(u << 16); }
; DI float hi16(unsigned u) { return __uint_as_float(u & 0xffff0000u); }
; DI float sigmoidf_(float x) { return 1.f / (1.f + __expf(-x)); }
; DI void post_scan(const PX& p, int l, int M, unsigned char* smem) {
;     ...
;       for (int o = 8; o >= 1; o >>= 1) s += __shfl_xor(s, o);
;       const float mu = s * (1.f / 192.f);
;       float q = 0.f;
; #pragma unroll
;       for (int i = 0; i < 12; i++) { x[i] -= mu; q += x[i] * x[i]; }
; #pragma unroll
;       for (int o = 8; o >= 1; o >>= 1) q += __shfl_xor(q, o);
;       const float rs = rsqrtf(q * (1.f / 192.f) + 1e-5f);
;       const uint2* og = (const uint2*)(Zml + (size_t)r * 3072 + 2304 + lane * 12);
;       const float4* gg = (const float4*)(ng + lane * 12);
; #pragma unroll
;       for (int i = 0; i < 3; i++) {
;         const uint2 o = og[i];
;         const float4 g4 = ngv[i];
;         uint2 w_;
;         w_.x = pack2(x[4 * i] * rs * g4.x * sigmoidf_(lo16(o.x)), x[4 * i + 1] * rs * g4.y * sigmoidf_(hi16(o.x)));
;         w_.y = pack2(x[4 * i + 2] * rs * g4.z * sigmoidf_(lo16(o.y)), x[4 * i + 3] * rs * g4.w * sigmoidf_(hi16(o.y)));
;         ((uint2*)(Hf + ro))[i] = w_;
;       }
	v_add_f32_e32 v42, v42, v46
	ds_bpermute_b32 v46, v65, v42
	s_waitcnt lgkmcnt(0)
	v_add_f32_e32 v42, v42, v46
	ds_bpermute_b32 v46, v66, v42
	s_waitcnt lgkmcnt(0)
	v_add_f32_e32 v42, v42, v46
	v_mul_f32_e32 v42, 0x3baaaaab, v42
	v_pk_add_f32 v[48:49], v[40:41], v[42:43] op_sel_hi:[1,0] neg_lo:[0,1] neg_hi:[0,1]
	v_pk_add_f32 v[52:53], v[38:39], v[42:43] op_sel_hi:[1,0] neg_lo:[0,1] neg_hi:[0,1]
	v_pk_mul_f32 v[50:51], v[48:49], v[48:49]
	v_mov_b32_e32 v46, v43
	v_pk_mul_f32 v[60:61], v[52:53], v[52:53]
	v_pk_add_f32 v[40:41], v[46:47], v[42:43] op_sel_hi:[1,0] neg_lo:[0,1] neg_hi:[0,1]
	v_add_f32_e32 v46, v50, v51
	v_pk_add_f32 v[68:69], v[44:45], v[42:43] op_sel_hi:[1,0] neg_lo:[0,1] neg_hi:[0,1]
	v_add_f32_e32 v46, v60, v46
	v_pk_mul_f32 v[70:71], v[68:69], v[68:69]
	v_add_f32_e32 v46, v61, v46
	v_pk_add_f32 v[44:45], v[58:59], v[42:43] op_sel_hi:[1,0] neg_lo:[0,1] neg_hi:[0,1]
	v_add_f32_e32 v46, v70, v46
	v_pk_mul_f32 v[58:59], v[44:45], v[44:45]
	v_add_f32_e32 v46, v71, v46
	v_add_f32_e32 v46, v58, v46
	v_pk_add_f32 v[38:39], v[56:57], v[42:43] op_sel_hi:[1,0] neg_lo:[0,1] neg_hi:[0,1]
	v_pk_mul_f32 v[42:43], v[40:41], v[40:41]
	v_add_f32_e32 v46, v59, v46
	v_add_f32_e32 v42, v42, v46
	v_pk_mul_f32 v[56:57], v[38:39], v[38:39]
	v_add_f32_e32 v42, v43, v42
	v_add_f32_e32 v42, v57, v42
	v_add_f32_e32 v42, v56, v42
	ds_bpermute_b32 v43, v63, v42
	s_waitcnt lgkmcnt(0)
	v_add_f32_e32 v42, v42, v43
	ds_bpermute_b32 v43, v64, v42
	s_waitcnt lgkmcnt(0)
	v_add_f32_e32 v42, v42, v43
	ds_bpermute_b32 v43, v65, v42
	s_waitcnt lgkmcnt(0)
	v_add_f32_e32 v42, v42, v43
	ds_bpermute_b32 v43, v66, v42
	s_waitcnt lgkmcnt(0)
	v_add_f32_e32 v42, v42, v43
	v_mov_b32_e32 v43, 0x3727c5ac
	v_fmamk_f32 v42, v42, 0x3baaaaab, v43
	v_cmp_gt_f32_e32 vcc, s1, v42
	v_mul_f32_e32 v43, 0x4b800000, v42
	s_mov_b32 s1, 0x36218000
	v_cndmask_b32_e32 v42, v42, v43, vcc
	v_rsq_f32_e32 v42, v42
	s_nop 0
	v_mul_f32_e32 v43, 0x45800000, v42
	v_cndmask_b32_e32 v42, v42, v43, vcc
	v_pk_mul_f32 v[46:47], v[48:49], v[42:43] op_sel_hi:[1,0]
	s_nop 0
	v_pk_mul_f32 v[46:47], v[6:7], v[46:47]
	s_nop 0
	v_pk_mul_f32 v[36:37], v[36:37], v[46:47]
	v_pk_mul_f32 v[46:47], v[52:53], v[42:43] op_sel_hi:[1,0]
	v_cvt_pk_bf16_f32 v36, v36, v37
	v_pk_mul_f32 v[46:47], v[8:9], v[46:47]
	s_nop 0
	v_pk_mul_f32 v[46:47], v[54:55], v[46:47]
	s_nop 0
	v_cvt_pk_bf16_f32 v37, v46, v47
	global_store_dwordx2 v[32:33], v[36:37], off offset:256
	s_waitcnt vmcnt(11)
	v_mov_b64_e32 v[36:37], v[100:101]
	v_lshlrev_b32_e32 v43, 16, v36
	v_and_b32_e32 v36, 0xffff0000, v36
	v_mul_f32_e32 v43, 0xbfb8aa3b, v43
	v_mul_f32_e32 v36, 0xbfb8aa3b, v36
	v_exp_f32_e32 v46, v43
	v_exp_f32_e32 v47, v36
	v_pk_mul_f32 v[48:49], v[68:69], v[42:43] op_sel_hi:[1,0]
	v_pk_add_f32 v[46:47], v[46:47], 1.0 op_sel_hi:[1,0]
	s_nop 0
	v_div_scale_f32 v36, s[2:3], v47, v47, 1.0
	v_rcp_f32_e32 v43, v36
	v_pk_mul_f32 v[48:49], v[2:3], v[48:49]
	v_fma_f32 v50, -v36, v43, 1.0
	v_fmac_f32_e32 v43, v50, v43
	v_div_scale_f32 v50, vcc, 1.0, v47, 1.0
	v_mul_f32_e32 v51, v50, v43
	v_fma_f32 v52, -v36, v51, v50
	v_fmac_f32_e32 v51, v52, v43
	v_fma_f32 v36, -v36, v51, v50
	v_div_fmas_f32 v36, v36, v43, v51
	v_div_fixup_f32 v47, v36, v47, 1.0
	v_div_scale_f32 v36, s[2:3], v46, v46, 1.0
	v_rcp_f32_e32 v43, v36
	s_nop 0
	v_fma_f32 v50, -v36, v43, 1.0
	v_fmac_f32_e32 v43, v50, v43
	v_div_scale_f32 v50, vcc, 1.0, v46, 1.0
	v_mul_f32_e32 v51, v50, v43
	v_fma_f32 v52, -v36, v51, v50
	v_fmac_f32_e32 v51, v52, v43
	v_fma_f32 v36, -v36, v51, v50
	v_div_fmas_f32 v36, v36, v43, v51
	v_div_fixup_f32 v46, v36, v46, 1.0
	v_lshlrev_b32_e32 v43, 16, v37
	v_and_b32_e32 v37, 0xffff0000, v37
	v_pk_mul_f32 v[46:47], v[46:47], v[48:49]
	v_mul_f32_e32 v43, 0xbfb8aa3b, v43
	v_mul_f32_e32 v37, 0xbfb8aa3b, v37
	v_cvt_pk_bf16_f32 v36, v46, v47
	v_exp_f32_e32 v46, v43
	v_exp_f32_e32 v47, v37
	v_pk_mul_f32 v[44:45], v[44:45], v[42:43] op_sel_hi:[1,0]
	v_pk_add_f32 v[46:47], v[46:47], 1.0 op_sel_hi:[1,0]
	s_nop 0
	v_div_scale_f32 v37, s[2:3], v47, v47, 1.0
	v_rcp_f32_e32 v43, v37
	v_pk_mul_f32 v[44:45], v[4:5], v[44:45]
	v_fma_f32 v48, -v37, v43, 1.0
	v_fmac_f32_e32 v43, v48, v43
	v_div_scale_f32 v48, vcc, 1.0, v47, 1.0
	v_mul_f32_e32 v49, v48, v43
	v_fma_f32 v50, -v37, v49, v48
	v_fmac_f32_e32 v49, v50, v43
	v_fma_f32 v37, -v37, v49, v48
	v_div_fmas_f32 v37, v37, v43, v49
	v_div_fixup_f32 v47, v37, v47, 1.0
	v_div_scale_f32 v37, s[2:3], v46, v46, 1.0
	v_rcp_f32_e32 v43, v37
	s_nop 0
	v_fma_f32 v48, -v37, v43, 1.0
	v_fmac_f32_e32 v43, v48, v43
	v_div_scale_f32 v48, vcc, 1.0, v46, 1.0
	v_mul_f32_e32 v49, v48, v43
	v_fma_f32 v50, -v37, v49, v48
	v_fmac_f32_e32 v49, v50, v43
	v_fma_f32 v37, -v37, v49, v48
	v_div_fmas_f32 v37, v37, v43, v49
	v_div_fixup_f32 v46, v37, v46, 1.0
	v_pk_mul_f32 v[44:45], v[46:47], v[44:45]
	v_pk_mul_f32 v[40:41], v[40:41], v[42:43] op_sel_hi:[1,0]
	v_cvt_pk_bf16_f32 v37, v44, v45
	global_store_dwordx2 v[32:33], v[36:37], off offset:264
	v_pk_mul_f32 v[40:41], v[10:11], v[40:41]
	s_waitcnt vmcnt(11)
; DI unsigned pack2(float a, float b) { f32x2_t v = {a, b}; bf16x2_t r = __builtin_convertvector(v, bf16x2_t); return __builtin_bit_cast(unsigned, r); }
; DI float lo16(unsigned u) { return __uint_as_float(u << 16); }
; DI float hi16(unsigned u) { return __uint_as_float(u & 0xffff0000u); }
; DI float sigmoidf_(float x) { return 1.f / (1.f + __expf(-x)); }
; DI void post_scan(const PX& p, int l, int M, unsigned char* smem) {
;     ...
;       for (int i = 0; i < 3; i++) {
;         const uint2 o = og[i];
;         const float4 g4 = ngv[i];
;         uint2 w_;
;         w_.x = pack2(x[4 * i] * rs * g4.x * sigmoidf_(lo16(o.x)), x[4 * i + 1] * rs * g4.y * sigmoidf_(hi16(o.x)));
;         w_.y = pack2(x[4 * i + 2] * rs * g4.z * sigmoidf_(lo16(o.y)), x[4 * i + 3] * rs * g4.w * sigmoidf_(hi16(o.y)));
;         ((uint2*)(Hf + ro))[i] = w_;
;       }
;     ...
;       for (int i = 0; i < 3; i++) {
;         const uint2 a = yf[i], bq = yb[i], u = zu[i];
;         const float4 d4 = sdv[i];
;         float y[4];
;         y[0] = lo16(a.x) + lo16(bq.x) + d4.x * lo16(u.x);
;         y[1] = hi16(a.x) + hi16(bq.x) + d4.y * hi16(u.x);
;         y[2] = lo16(a.y) + lo16(bq.y) + d4.z * lo16(u.y);
;         y[3] = hi16(a.y) + hi16(bq.y) + d4.w * hi16(u.y);
; #pragma unroll
;         for (int j = 0; j < 4; j++) {
;           const float uu = 0.7978845608028654f * (y[j] + 0.044715f * y[j] * y[j] * y[j]);
;           y[j] = 0.5f * y[j] * (1.f + tanhf(uu));
	v_mov_b64_e32 v[34:35], v[102:103]
	v_lshlrev_b32_e32 v36, 16, v34
	v_and_b32_e32 v34, 0xffff0000, v34
	v_mul_f32_e32 v36, 0xbfb8aa3b, v36
	v_mul_f32_e32 v34, 0xbfb8aa3b, v34
	v_exp_f32_e32 v36, v36
	v_exp_f32_e32 v37, v34
	s_nop 0
	v_pk_add_f32 v[36:37], v[36:37], 1.0 op_sel_hi:[1,0]
	s_nop 0
	v_div_scale_f32 v34, s[2:3], v37, v37, 1.0
	v_rcp_f32_e32 v43, v34
	s_nop 0
	v_fma_f32 v44, -v34, v43, 1.0
	v_fmac_f32_e32 v43, v44, v43
	v_div_scale_f32 v44, vcc, 1.0, v37, 1.0
	v_mul_f32_e32 v45, v44, v43
	v_fma_f32 v46, -v34, v45, v44
	v_fmac_f32_e32 v45, v46, v43
	v_fma_f32 v34, -v34, v45, v44
	v_div_fmas_f32 v34, v34, v43, v45
	v_div_fixup_f32 v37, v34, v37, 1.0
	v_div_scale_f32 v34, s[2:3], v36, v36, 1.0
	v_rcp_f32_e32 v43, v34
	s_nop 0
	v_fma_f32 v44, -v34, v43, 1.0
	v_fmac_f32_e32 v43, v44, v43
	v_div_scale_f32 v44, vcc, 1.0, v36, 1.0
	v_mul_f32_e32 v45, v44, v43
	v_fma_f32 v46, -v34, v45, v44
	v_fmac_f32_e32 v45, v46, v43
	v_fma_f32 v34, -v34, v45, v44
	v_div_fmas_f32 v34, v34, v43, v45
	v_div_fixup_f32 v36, v34, v36, 1.0
	v_pk_mul_f32 v[36:37], v[36:37], v[40:41]
	v_pk_mul_f32 v[38:39], v[38:39], v[42:43] op_sel_hi:[1,0]
	v_cvt_pk_bf16_f32 v34, v36, v37
	v_lshlrev_b32_e32 v36, 16, v35
	v_and_b32_e32 v35, 0xffff0000, v35
	v_mul_f32_e32 v36, 0xbfb8aa3b, v36
	v_mul_f32_e32 v35, 0xbfb8aa3b, v35
	v_exp_f32_e32 v36, v36
	v_exp_f32_e32 v37, v35
	v_pk_mul_f32 v[38:39], v[12:13], v[38:39] op_sel:[0,1] op_sel_hi:[1,0]
	v_pk_add_f32 v[36:37], v[36:37], 1.0 op_sel_hi:[1,0]
	s_nop 0
	v_div_scale_f32 v35, s[2:3], v37, v37, 1.0
	v_rcp_f32_e32 v40, v35
	s_nop 0
	v_fma_f32 v41, -v35, v40, 1.0
	v_fmac_f32_e32 v40, v41, v40
	v_div_scale_f32 v41, vcc, 1.0, v37, 1.0
	v_mul_f32_e32 v42, v41, v40
	v_fma_f32 v43, -v35, v42, v41
	v_fmac_f32_e32 v42, v43, v40
	v_fma_f32 v35, -v35, v42, v41
	v_div_fmas_f32 v35, v35, v40, v42
	v_div_fixup_f32 v37, v35, v37, 1.0
	v_div_scale_f32 v35, s[2:3], v36, v36, 1.0
	v_rcp_f32_e32 v40, v35
	s_nop 0
	v_fma_f32 v41, -v35, v40, 1.0
	v_fmac_f32_e32 v40, v41, v40
	v_div_scale_f32 v41, vcc, 1.0, v36, 1.0
	v_mul_f32_e32 v42, v41, v40
	v_fma_f32 v43, -v35, v42, v41
	v_fmac_f32_e32 v42, v43, v40
	v_fma_f32 v35, -v35, v42, v41
	v_div_fmas_f32 v35, v35, v40, v42
	v_div_fixup_f32 v36, v35, v36, 1.0
	v_pk_mul_f32 v[36:37], v[36:37], v[38:39]
	s_nop 0
	v_cvt_pk_bf16_f32 v35, v36, v37
	global_store_dwordx2 v[32:33], v[34:35], off offset:272
	v_add_co_u32_e32 v32, vcc, s1, v30
	s_mov_b32 s1, 0x39818000
	s_nop 0
	v_addc_co_u32_e32 v33, vcc, 0, v31, vcc
	v_add_co_u32_e32 v34, vcc, s1, v30
	s_mov_b32 s1, 0x28a18000
	s_nop 0
	v_addc_co_u32_e32 v35, vcc, 0, v31, vcc
	v_add_co_u32_e32 v36, vcc, s1, v30
	v_addc_co_u32_e32 v37, vcc, 0, v31, vcc
	s_mov_b32 s1, 0x3f200000
	s_waitcnt vmcnt(11)
	v_mov_b64_e32 v[38:39], v[104:105]
	v_lshlrev_b32_e32 v44, 16, v38
	s_waitcnt vmcnt(10)
	v_mov_b64_e32 v[40:41], v[106:107]
	v_lshlrev_b32_e32 v45, 16, v40
	v_add_f32_e32 v44, v45, v44
	s_waitcnt vmcnt(9)
	v_mov_b64_e32 v[42:43], v[108:109]
	v_lshlrev_b32_e32 v45, 16, v42
	v_fmac_f32_e32 v44, v14, v45
	v_mul_f32_e32 v45, 0x3d372713, v44
	v_mul_f32_e32 v45, v44, v45
	v_fma_f32 v45, v44, v45, v44
	v_mul_f32_e32 v45, 0x3f4c422a, v45
	v_cmp_nlt_f32_e64 s[2:3], |v45|, s1
	s_and_saveexec_b64 s[12:13], s[2:3]
	s_xor_b64 s[12:13], exec, s[12:13]
	s_cbranch_execz .LBB0_373
	v_add_f32_e64 v46, |v45|, |v45|
	v_mul_f32_e32 v47, 0x3fb8aa3b, v46
	v_rndne_f32_e32 v48, v47
	s_mov_b32 s2, 0x3fb8aa3b
	v_sub_f32_e32 v49, v47, v48
	v_fma_f32 v47, v46, s2, -v47
	v_fmac_f32_e32 v47, 0x32a5705f, v46
	v_add_f32_e32 v47, v49, v47
	v_cvt_i32_f32_e32 v48, v48
	v_exp_f32_e32 v47, v47
	s_mov_b32 s2, 0xc2ce8ed0
	v_cmp_ngt_f32_e32 vcc, s2, v46
	s_mov_b32 s2, 0x42b17218
	v_ldexp_f32 v47, v47, v48
	v_cndmask_b32_e32 v47, 0, v47, vcc
	v_cmp_nlt_f32_e32 vcc, s2, v46
	s_nop 1
	v_cndmask_b32_e32 v46, v212, v47, vcc
	v_add_f32_e32 v46, 1.0, v46
	v_rcp_f32_e32 v46, v46
	s_nop 0
	v_fma_f32 v46, v46, -2.0, 1.0

; DI unsigned pack2(float a, float b) { f32x2_t v = {a, b}; bf16x2_t r = __builtin_convertvector(v, bf16x2_t); return __builtin_bit_cast(unsigned, r); }
; DI void post_scan(const PX& p, int l, int M, unsigned char* smem) {
;     ...
; #pragma unroll
;         for (int j = 0; j < 4; j++) {
;           const float uu = 0.7978845608028654f * (y[j] + 0.044715f * y[j] * y[j] * y[j]);
;           y[j] = 0.5f * y[j] * (1.f + tanhf(uu));
;         }
;         uint2 w_;
;         w_.x = pack2(y[0], y[1]); w_.y = pack2(y[2], y[3]);
;         ((uint2*)(Yf + ro))[i] = w_;
.LBB0_385:
	s_andn2_saveexec_b64 s[12:13], s[12:13]
	v_mul_f32_e32 v43, v39, v39
	v_mov_b32_e32 v50, 0x3ca908c9
	v_fmamk_f32 v50, v43, 0xbbbac73d, v50
	v_fmaak_f32 v50, v43, v50, 0xbd5c1c4e
	v_fmaak_f32 v50, v43, v50, 0x3e088382
	v_fmaak_f32 v50, v43, v50, 0xbeaaaa99
	v_mul_f32_e64 v50, |v39|, v50
	v_fma_f32 v43, v43, v50, |v39|
	s_or_b64 exec, exec, s[12:13]
	s_mov_b64 s[2:3], 0x36218100
	v_lshl_add_u64 v[50:51], v[30:31], 0, s[2:3]
	s_brev_b32 s2, -2
	v_bfi_b32 v48, s2, v49, v48
	v_bfi_b32 v45, s2, v46, v45
	v_bfi_b32 v40, s2, v42, v40
	v_bfi_b32 v39, s2, v43, v39
	v_mul_f32_e32 v47, 0.5, v47
	v_add_f32_e32 v48, 1.0, v48
	v_mul_f32_e32 v41, 0.5, v41
	v_mul_f32_e32 v44, 0.5, v44
	v_add_f32_e32 v45, 1.0, v45
	v_mul_f32_e32 v38, 0.5, v38
	v_add_f32_e32 v40, 1.0, v40
	v_add_f32_e32 v39, 1.0, v39
	v_mul_f32_e32 v47, v47, v48
	v_mul_f32_e32 v44, v44, v45
	v_mul_f32_e32 v38, v38, v40
	v_mul_f32_e32 v39, v41, v39
	v_cvt_pk_bf16_f32 v38, v44, v38
	v_cvt_pk_bf16_f32 v39, v47, v39
	global_store_dwordx2 v[50:51], v[38:39], off
	s_nop 0
	s_waitcnt vmcnt(9)
	v_mov_b64_e32 v[38:39], v[110:111]
	v_lshlrev_b32_e32 v44, 16, v38
	s_waitcnt vmcnt(8)
	v_mov_b64_e32 v[40:41], v[112:113]
	v_lshlrev_b32_e32 v45, 16, v40
	v_add_f32_e32 v44, v45, v44
	s_waitcnt vmcnt(7)
	v_mov_b64_e32 v[42:43], v[114:115]
	v_lshlrev_b32_e32 v45, 16, v42
	v_fmac_f32_e32 v44, v18, v45
	v_mul_f32_e32 v45, 0x3d372713, v44
	v_mul_f32_e32 v45, v44, v45
	v_fma_f32 v45, v44, v45, v44
	v_mul_f32_e32 v45, 0x3f4c422a, v45
	v_cmp_nlt_f32_e64 s[2:3], |v45|, s1
	s_and_saveexec_b64 s[12:13], s[2:3]
	s_xor_b64 s[12:13], exec, s[12:13]
	s_cbranch_execz .LBB0_389
	v_add_f32_e64 v46, |v45|, |v45|
	v_mul_f32_e32 v47, 0x3fb8aa3b, v46
	v_rndne_f32_e32 v48, v47
	s_mov_b32 s2, 0x3fb8aa3b
	v_sub_f32_e32 v49, v47, v48
	v_fma_f32 v47, v46, s2, -v47
	v_fmac_f32_e32 v47, 0x32a5705f, v46
	v_add_f32_e32 v47, v49, v47
	v_cvt_i32_f32_e32 v48, v48
	v_exp_f32_e32 v47, v47
	s_mov_b32 s2, 0xc2ce8ed0
	v_cmp_ngt_f32_e32 vcc, s2, v46
	s_mov_b32 s2, 0x42b17218
	v_ldexp_f32 v47, v47, v48
	v_cndmask_b32_e32 v47, 0, v47, vcc
	v_cmp_nlt_f32_e32 vcc, s2, v46
	s_nop 1
	v_cndmask_b32_e32 v46, v212, v47, vcc
	v_add_f32_e32 v46, 1.0, v46
	v_rcp_f32_e32 v46, v46
	s_nop 0
	v_fma_f32 v46, v46, -2.0, 1.0

; DI unsigned pack2(float a, float b) { f32x2_t v = {a, b}; bf16x2_t r = __builtin_convertvector(v, bf16x2_t); return __builtin_bit_cast(unsigned, r); }
; DI float lo16(unsigned u) { return __uint_as_float(u << 16); }
; DI float hi16(unsigned u) { return __uint_as_float(u & 0xffff0000u); }
; DI void post_scan(const PX& p, int l, int M, unsigned char* smem) {
;     ...
;       for (int i = 0; i < 3; i++) {
;         const uint2 a = yf[i], bq = yb[i], u = zu[i];
;         const float4 d4 = sdv[i];
;         float y[4];
;         y[0] = lo16(a.x) + lo16(bq.x) + d4.x * lo16(u.x);
;         y[1] = hi16(a.x) + hi16(bq.x) + d4.y * hi16(u.x);
;         y[2] = lo16(a.y) + lo16(bq.y) + d4.z * lo16(u.y);
;         y[3] = hi16(a.y) + hi16(bq.y) + d4.w * hi16(u.y);
; #pragma unroll
;         for (int j = 0; j < 4; j++) {
;           const float uu = 0.7978845608028654f * (y[j] + 0.044715f * y[j] * y[j] * y[j]);
;           y[j] = 0.5f * y[j] * (1.f + tanhf(uu));
;         }
;         uint2 w_;
;         w_.x = pack2(y[0], y[1]); w_.y = pack2(y[2], y[3]);
;         ((uint2*)(Yf + ro))[i] = w_;
.LBB0_401:
	s_andn2_saveexec_b64 s[12:13], s[12:13]
	v_mul_f32_e32 v43, v41, v41
	v_mov_b32_e32 v50, 0x3ca908c9
	v_fmamk_f32 v50, v43, 0xbbbac73d, v50
	v_fmaak_f32 v50, v43, v50, 0xbd5c1c4e
	v_fmaak_f32 v50, v43, v50, 0x3e088382
	v_fmaak_f32 v50, v43, v50, 0xbeaaaa99
	v_mul_f32_e64 v50, |v41|, v50
	v_fma_f32 v43, v43, v50, |v41|
	s_or_b64 exec, exec, s[12:13]
	s_nop 0
	s_nop 0
	s_brev_b32 s12, -2
	v_bfi_b32 v48, s12, v49, v48
	v_bfi_b32 v45, s12, v46, v45
	v_bfi_b32 v40, s12, v42, v40
	v_bfi_b32 v41, s12, v43, v41
	v_mul_f32_e32 v47, 0.5, v47
	v_mul_f32_e32 v49, 0.5, v39
	v_mul_f32_e32 v44, 0.5, v44
	v_mul_f32_e32 v46, 0.5, v38
	v_add_f32_e32 v42, 1.0, v48
	v_add_f32_e32 v43, 1.0, v45
	v_add_f32_e32 v40, 1.0, v40
	v_add_f32_e32 v41, 1.0, v41
	s_mov_b64 s[2:3], 0x36218108
	v_mul_f32_e32 v42, v47, v42
	v_mul_f32_e32 v43, v44, v43
	v_mul_f32_e32 v40, v46, v40
	v_mul_f32_e32 v41, v49, v41
	v_lshl_add_u64 v[38:39], v[30:31], 0, s[2:3]
	v_cvt_pk_bf16_f32 v40, v43, v40
	v_cvt_pk_bf16_f32 v41, v42, v41
	global_store_dwordx2 v[38:39], v[40:41], off
	s_waitcnt vmcnt(7)
	v_mov_b64_e32 v[32:33], v[116:117]
	v_lshlrev_b32_e32 v38, 16, v32
	s_waitcnt vmcnt(6)
	v_mov_b64_e32 v[34:35], v[118:119]
	v_lshlrev_b32_e32 v39, 16, v34
	v_add_f32_e32 v38, v39, v38
	s_waitcnt vmcnt(5)
	v_mov_b64_e32 v[36:37], v[120:121]
	v_lshlrev_b32_e32 v39, 16, v36
	v_fmac_f32_e32 v38, v22, v39
	v_mul_f32_e32 v39, 0x3d372713, v38
	v_mul_f32_e32 v39, v38, v39
	v_fma_f32 v39, v38, v39, v38
	v_mul_f32_e32 v39, 0x3f4c422a, v39
	v_cmp_nlt_f32_e64 s[2:3], |v39|, s1
	s_and_saveexec_b64 s[12:13], s[2:3]
	s_xor_b64 s[12:13], exec, s[12:13]
	s_cbranch_execz .LBB0_405
	v_add_f32_e64 v40, |v39|, |v39|
	v_mul_f32_e32 v41, 0x3fb8aa3b, v40
	v_rndne_f32_e32 v42, v41
	s_mov_b32 s2, 0x3fb8aa3b
	v_sub_f32_e32 v43, v41, v42
	v_fma_f32 v41, v40, s2, -v41
	v_fmac_f32_e32 v41, 0x32a5705f, v40
	v_add_f32_e32 v41, v43, v41
	v_cvt_i32_f32_e32 v42, v42
	v_exp_f32_e32 v41, v41
	s_mov_b32 s2, 0xc2ce8ed0
	v_cmp_ngt_f32_e32 vcc, s2, v40
	s_mov_b32 s2, 0x42b17218
	v_ldexp_f32 v41, v41, v42
	v_cndmask_b32_e32 v41, 0, v41, vcc
	v_cmp_nlt_f32_e32 vcc, s2, v40
	s_nop 1
	v_cndmask_b32_e32 v40, v212, v41, vcc
	v_add_f32_e32 v40, 1.0, v40
	v_rcp_f32_e32 v40, v40
	s_nop 0
	v_fma_f32 v40, v40, -2.0, 1.0

; DI void mlstm_job(const PX& p, int l, int job, unsigned char* smem) {
;     ...
;   const float gbi = p.in[19][l * 16 + (dir ? 8 : 0) + h];
;   const float gbf = p.in[19][l * 16 + (dir ? 12 : 4) + h];
;   f32x16 st[6];
; #pragma unroll
;   for (int i = 0; i < 6; i++)
; #pragma unroll
;     for (int r = 0; r < 16; r++) st[i][r] = 0.f;
;   float m = 0.f;
;   float pgi = 0.f, pgf = 0.f;
;   if (w == 0) {
;     const int t = dir ? 255 - lane : lane;
;     const int tok = NLAT + b * 256 + t;
;     pgi = Zgt[(size_t)tok * 16 + (dir ? 8 : 0) + h];
;     pgf = Zgt[(size_t)tok * 16 + (dir ? 12 : 4) + h];
;   }
.LBB0_445:
	s_or_b64 exec, exec, s[4:5]
	s_sub_i32 s1, s38, 48
	s_and_b32 s2, s38, 1
	s_lshr_b32 s3, s1, 3
	s_lshl_b32 s1, s2, 3
	s_or_b32 s4, s1, s39
	s_or_b32 s4, s4, s0
	s_ashr_i32 s5, s4, 31
	v_readlane_b32 s8, v252, 35
	s_lshl_b64 s[4:5], s[4:5], 2
	v_readlane_b32 s14, v252, 41
	v_readlane_b32 s15, v252, 42
	s_add_u32 s6, s14, s4
	s_addc_u32 s7, s15, s5
	s_cmp_eq_u32 s2, 0
	s_cselect_b64 s[4:5], -1, 0
	global_load_dword v161, v1, s[6:7]
	s_and_b64 s[6:7], s[4:5], exec
	s_cselect_b32 s2, 4, 12
	s_or_b32 s6, s0, s39
	s_or_b32 s6, s6, s2
	s_ashr_i32 s7, s6, 31
	s_lshl_b64 s[6:7], s[6:7], 2
	s_add_u32 s6, s14, s6
	s_addc_u32 s7, s15, s7
	global_load_dword v174, v1, s[6:7]
	v_readlane_b32 s9, v252, 36
	v_cmp_gt_u32_e32 vcc, 0x1c0, v160
	s_nop 1
	s_xor_b64 s[6:7], vcc, -1
	v_mov_b32_e32 v163, 0
	v_mov_b32_e32 v180, 0
	v_mov_b32_e32 v177, 0
	v_readlane_b32 s10, v252, 37
	v_readlane_b32 s11, v252, 38
	v_readlane_b32 s12, v252, 39
	v_readlane_b32 s13, v252, 40
	v_readlane_b32 s16, v252, 43
	v_readlane_b32 s17, v252, 44
	v_readlane_b32 s18, v252, 45
	v_readlane_b32 s19, v252, 46
	v_readlane_b32 s20, v252, 47
	v_readlane_b32 s21, v252, 48
	v_readlane_b32 s22, v252, 49
	v_readlane_b32 s23, v252, 50
	s_and_saveexec_b64 s[8:9], s[6:7]
	s_cbranch_execz .LBB0_447
	v_and_b32_e32 v0, 63, v160
	v_lshlrev_b32_e32 v0, 4, v0
	s_lshl_b32 s10, s3, 12
	v_xor_b32_e32 v2, 0xff0, v0
	v_cndmask_b32_e64 v0, v2, v0, s[4:5]
	s_add_i32 s10, s10, 0x80000
	v_or_b32_e32 v4, s10, v0
	s_or_b32 s10, s0, s1
	v_readlane_b32 s12, v254, 14
	v_or_b32_e32 v0, s10, v4
	v_readlane_b32 s13, v254, 15
	s_or_b32 s10, s2, s0
	s_nop 0
	v_lshl_add_u64 v[2:3], v[0:1], 2, s[12:13]
	v_or_b32_e32 v0, s10, v4
	global_load_dword v177, v[2:3], off
	v_lshl_add_u64 v[2:3], v[0:1], 2, s[12:13]
	global_load_dword v180, v[2:3], off
.LBB0_447:
	s_or_b64 exec, exec, s[8:9]
	v_and_b32_e32 v175, 63, v160
	v_mov_b32_e32 v0, 0x1da00
	v_bfe_u32 v5, v160, 5, 1
	s_and_b64 s[8:9], s[4:5], exec
	v_lshl_or_b32 v178, v175, 2, v0
	v_mov_b32_e32 v0, 0x13400
	v_ashrrev_i32_e32 v2, 2, v160
	s_movk_i32 s16, 0xffe0
	v_ashrrev_i32_e32 v3, 6, v160
	s_mov_b32 s8, 0x32c18100
	v_lshl_or_b32 v179, v175, 1, v0
	v_mul_i32_i24_e32 v0, 0xfffffe72, v175
	s_movk_i32 s37, 0x190
	v_and_b32_e32 v9, 0xffffffe0, v2
	v_bfi_b32 v4, s16, v2, v160
	v_lshlrev_b32_e32 v2, 4, v5
	v_and_b32_e32 v176, 31, v160
	s_cselect_b32 s8, 0x2f618100, s8
	v_mad_u32_u24 v181, v175, s37, v0
	v_bfrev_b32_e32 v0, 0.5
	v_mad_u64_u32 v[164:165], s[16:17], v4, s37, v[2:3]
	v_lshlrev_b32_e32 v4, 5, v3
	s_add_u32 s13, s96, s8
	v_lshl_or_b32 v183, v211, 2, v0
	v_lshlrev_b32_e32 v0, 3, v5
	v_and_or_b32 v10, v4, 32, v176
	v_lshl_or_b32 v185, v5, 2, v9
	v_mov_b32_e32 v5, 0x1b200
	s_movk_i32 s36, 0x90
	s_addc_u32 s20, s97, 0
	s_lshl_b32 s12, s3, 8
	v_mad_u32_u24 v9, v10, s36, v5
	v_or_b32_e32 v5, v4, v176
	s_lshl_b32 s11, s3, 11
	s_add_i32 s12, s12, 0x8000
	s_mul_i32 s3, s0, 0x180
	v_readlane_b32 s8, v254, 2
	v_mul_lo_u32 v5, v5, s36
	s_mov_b32 s16, 0x13400
	v_readlane_b32 s9, v254, 3
	s_add_u32 s74, s8, s3
	v_add3_u32 v187, v5, v2, s16
	v_cmp_eq_u32_e64 s[18:19], 6, v3
	v_cmp_gt_u32_e64 s[16:17], 32, v175
	s_addc_u32 s75, s9, 0
	s_and_b64 s[60:61], s[18:19], s[16:17]
	s_add_u32 s18, s13, s3
	s_movk_i32 s8, 0x18e
	v_mov_b32_e32 v11, 0x1d800
	s_addc_u32 s19, s20, 0
	v_ashrrev_i32_e32 v5, 31, v4
	v_mad_u32_u24 v6, v175, s8, v181
	v_cmp_gt_i32_e64 s[8:9], 7, v3
	v_cmp_gt_i32_e64 s[44:45], 4, v3
	v_cmp_gt_i32_e64 s[14:15], 6, v3
	v_mad_u32_u24 v165, v10, s37, v2
	v_lshl_or_b32 v184, v10, 2, v11
	v_or_b32_e32 v11, 0x1b200, v2
	v_lshl_add_u64 v[2:3], v[4:5], 1, s[18:19]
	v_and_b32_e32 v8, 64, v211
	v_lshl_add_u64 v[166:167], v[2:3], 0, v[0:1]
	v_add_u32_e32 v2, -1, v211
	v_cmp_lt_i32_e64 s[18:19], v2, v8
	v_writelane_b32 v255, s14, 27
	v_or_b32_e32 v229, 3, v185
	v_cndmask_b32_e64 v2, v2, v211, s[18:19]
	v_lshlrev_b32_e32 v190, 2, v2
	v_add_u32_e32 v2, -2, v211
	v_cmp_lt_i32_e64 s[18:19], v2, v8
	v_writelane_b32 v255, s15, 28
	v_or_b32_e32 v230, 2, v185
	v_cndmask_b32_e64 v2, v2, v211, s[18:19]
	v_lshlrev_b32_e32 v191, 2, v2
	v_add_u32_e32 v2, -4, v211
	v_cmp_lt_i32_e64 s[20:21], v2, v8
	v_or_b32_e32 v232, 9, v185
	v_or_b32_e32 v233, 8, v185
	v_cndmask_b32_e64 v2, v2, v211, s[20:21]
	v_lshlrev_b32_e32 v192, 2, v2
	v_add_u32_e32 v2, -8, v211
	v_cmp_lt_i32_e64 s[22:23], v2, v8
	v_or_b32_e32 v234, 11, v185
	v_or_b32_e32 v235, 10, v185
	v_cndmask_b32_e64 v2, v2, v211, s[22:23]
	v_lshlrev_b32_e32 v193, 2, v2
	v_add_u32_e32 v2, -16, v211
	v_cmp_lt_i32_e64 s[24:25], v2, v8
	v_or_b32_e32 v237, 17, v185
	v_or_b32_e32 v238, 16, v185
	v_cndmask_b32_e64 v2, v2, v211, s[24:25]
	v_lshlrev_b32_e32 v194, 2, v2
	v_subrev_u32_e32 v2, 32, v211
	v_cmp_lt_i32_e64 s[26:27], v2, v8
	v_or_b32_e32 v239, 19, v185
	v_or_b32_e32 v240, 18, v185
	v_cndmask_b32_e64 v2, v2, v211, s[26:27]
	v_cmp_gt_i32_e64 s[26:27], v185, v10
	v_or_b32_e32 v242, 25, v185
	v_or_b32_e32 v243, 24, v185
	v_writelane_b32 v255, s26, 10
	v_or_b32_e32 v244, 27, v185
	v_or_b32_e32 v245, 26, v185
	v_writelane_b32 v255, s27, 11
	v_cmp_lt_i32_e64 s[26:27], v185, v10
	v_lshlrev_b32_e32 v195, 2, v2
	v_ashrrev_i32_e32 v2, 3, v160
	v_writelane_b32 v255, s26, 22
	v_add_u32_e32 v5, 0x200, v160
	v_and_b32_e32 v168, -8, v2
	v_writelane_b32 v255, s27, 23
	v_cmp_gt_i32_e64 s[26:27], v229, v10
	v_ashrrev_i32_e32 v5, 3, v5
	v_add_u32_e32 v13, 0x400, v160
	v_writelane_b32 v255, s26, 15
	v_or_b32_e32 v2, 7, v2
	v_lshlrev_b32_e32 v3, 2, v168
	v_writelane_b32 v255, s27, 16
	v_cmp_gt_i32_e64 s[26:27], v230, v10
	v_ashrrev_i32_e32 v13, 3, v13
	v_mul_lo_u32 v220, v2, s36
	v_writelane_b32 v255, s26, 18
	v_or_b32_e32 v2, 7, v5
	v_add_u32_e32 v196, 0x1e140, v3
; DI void mlstm_job(const PX& p, int l, int job, unsigned char* smem) {
;     ...
;   f32x16 st[6];
; #pragma unroll
;   for (int i = 0; i < 6; i++)
; #pragma unroll
;     for (int r = 0; r < 16; r++) st[i][r] = 0.f;
;   float m = 0.f;
;   float pgi = 0.f, pgf = 0.f;
;   if (w == 0) {
;     const int t = dir ? 255 - lane : lane;
;     const int tok = NLAT + b * 256 + t;
;     pgi = Zgt[(size_t)tok * 16 + (dir ? 8 : 0) + h];
;     pgf = Zgt[(size_t)tok * 16 + (dir ? 12 : 4) + h];
;   }
; #pragma unroll 1
	v_writelane_b32 v255, s27, 19
	v_cmp_gt_i32_e64 s[26:27], v232, v10
	v_lshlrev_b32_e32 v4, 1, v168
	v_and_b32_e32 v170, -8, v5
	v_writelane_b32 v255, s26, 29
	v_and_b32_e32 v172, -8, v13
	v_add_u32_e32 v202, 0x1e440, v3
	v_writelane_b32 v255, s27, 30
	v_cmp_gt_i32_e64 s[26:27], v233, v10
	v_mul_lo_u32 v224, v2, s36
	v_or_b32_e32 v2, 7, v13
	v_writelane_b32 v255, s26, 31
	v_mul_u32_u24_e32 v3, 0x90, v176
	v_mov_b32_e32 v30, v1
	v_writelane_b32 v255, s27, 32
	v_cmp_gt_i32_e64 s[26:27], v234, v10
	v_mov_b32_e32 v31, v1
	v_lshlrev_b32_e32 v7, 2, v176
	v_writelane_b32 v255, s26, 33
	v_add_u32_e32 v197, v6, v4
	v_lshlrev_b32_e32 v8, 2, v170
	v_writelane_b32 v255, s27, 34
	v_cmp_gt_i32_e64 s[26:27], v235, v10
	v_lshlrev_b32_e32 v12, 1, v170
	v_lshlrev_b32_e32 v14, 2, v172
	v_writelane_b32 v255, s26, 35
	v_lshlrev_b32_e32 v15, 1, v172
	v_mad_u32_u24 v203, v175, s37, v4
	v_writelane_b32 v255, s27, 36
	v_cmp_gt_i32_e64 s[26:27], v237, v10
	v_mul_lo_u32 v228, v2, s36
	v_mul_u32_u24_e32 v2, 0x190, v176
	v_writelane_b32 v255, s26, 37
	v_add3_u32 v247, v0, v0, v3
	v_or_b32_e32 v249, 32, v176
	v_writelane_b32 v255, s27, 38
	v_cmp_gt_i32_e64 s[26:27], v238, v10
	v_mov_b32_e32 v4, 0x1e040
	v_mov_b32_e32 v16, v1
	v_writelane_b32 v255, s26, 39
	v_mov_b32_e32 v17, v1
	v_mov_b32_e32 v18, v1
	v_writelane_b32 v255, s27, 40
	v_cmp_gt_i32_e64 s[26:27], v239, v10
	v_mov_b32_e32 v19, v1
	v_mov_b32_e32 v20, v1
	v_writelane_b32 v255, s26, 41
	v_mov_b32_e32 v21, v1
	v_mov_b32_e32 v22, v1
	v_writelane_b32 v255, s27, 42
	v_cmp_gt_i32_e64 s[26:27], v240, v10
	v_mov_b32_e32 v23, v1
	v_mov_b32_e32 v24, v1
	v_writelane_b32 v255, s26, 43
	v_mov_b32_e32 v25, v1
	v_mov_b32_e32 v26, v1
	v_writelane_b32 v255, s27, 44
	v_cmp_gt_i32_e64 s[26:27], v242, v10
	v_mov_b32_e32 v27, v1
	v_mov_b32_e32 v28, v1
	v_writelane_b32 v255, s26, 45
	v_mov_b32_e32 v29, v1
	v_mov_b64_e32 v[46:47], v[30:31]
	v_writelane_b32 v255, s27, 46
	v_cmp_gt_i32_e64 s[26:27], v243, v10
	v_mov_b64_e32 v[62:63], v[30:31]
	v_mov_b64_e32 v[78:79], v[30:31]
	v_writelane_b32 v255, s26, 47
	v_mov_b64_e32 v[94:95], v[30:31]
	v_mov_b64_e32 v[110:111], v[30:31]
	v_writelane_b32 v255, s27, 48
	v_cmp_gt_i32_e64 s[26:27], v244, v10
	s_mov_b32 s10, 0
	v_or_b32_e32 v182, 0x1dc00, v7
	v_writelane_b32 v255, s26, 49
	v_cmp_eq_u32_e64 s[14:15], 0, v175
	v_add_u32_e32 v189, 0x1e040, v7
	v_writelane_b32 v255, s27, 50
	v_cmp_gt_i32_e64 s[26:27], v245, v10
	v_cmp_gt_u32_e64 s[18:19], 2, v175
	v_cmp_gt_u32_e64 s[20:21], 4, v175
	v_writelane_b32 v255, s26, 51
	v_cmp_gt_u32_e64 s[22:23], 8, v175
	v_cmp_gt_u32_e64 s[24:25], 16, v175
	v_writelane_b32 v255, s27, 52
	v_readlane_b32 s26, v253, 31
	v_readlane_b32 s27, v253, 32
	s_lshl_b32 s26, s1, 2
	v_writelane_b32 v253, s26, 31
	v_ashrrev_i32_e32 v169, 31, v168
	v_ashrrev_i32_e32 v171, 31, v170
	v_add_u32_e32 v198, 0x1e140, v8
	v_add_u32_e32 v199, v6, v12
	v_ashrrev_i32_e32 v173, 31, v172
	v_add_u32_e32 v200, 0x1e140, v14
	v_add_u32_e32 v201, v6, v15
	v_mul_lo_u32 v219, v168, s36
	v_add_u32_e32 v221, 0x1e440, v8
	v_mad_u32_u24 v222, v175, s37, v12
	v_mul_lo_u32 v223, v170, s36
	v_add_u32_e32 v225, 0x1e440, v14
	v_mad_u32_u24 v226, v175, s37, v15
	v_mul_lo_u32 v227, v172, s36
	s_mov_b64 s[36:37], s[60:61]
	v_lshl_add_u32 v231, v185, 1, v9
	v_lshl_add_u32 v236, v233, 1, v9
	v_lshl_add_u32 v241, v238, 1, v9
	v_lshl_add_u32 v246, v243, 1, v9
	v_add_u32_e32 v248, 0xc800, v247
	v_lshl_add_u32 v250, v249, 2, v4
	v_or_b32_e32 v251, 0x1de00, v7
	s_xor_b64 s[76:77], vcc, -1
	v_writelane_b32 v253, s27, 32
	s_lshl_b32 s60, s0, 2
	s_lshl_b32 s68, s2, 2
	v_add_u32_e32 v215, v0, v2
	v_add_u32_e32 v216, v11, v3
	v_mov_b64_e32 v[44:45], v[28:29]
	v_mov_b64_e32 v[42:43], v[26:27]
	v_mov_b64_e32 v[40:41], v[24:25]
	v_mov_b64_e32 v[38:39], v[22:23]
	v_mov_b64_e32 v[36:37], v[20:21]
	v_mov_b64_e32 v[34:35], v[18:19]
	v_mov_b64_e32 v[32:33], v[16:17]
	v_mov_b64_e32 v[60:61], v[28:29]
	v_mov_b64_e32 v[58:59], v[26:27]
	v_mov_b64_e32 v[56:57], v[24:25]
	v_mov_b64_e32 v[54:55], v[22:23]
	v_mov_b64_e32 v[52:53], v[20:21]
	v_mov_b64_e32 v[50:51], v[18:19]
	v_mov_b64_e32 v[48:49], v[16:17]
	v_mov_b64_e32 v[76:77], v[28:29]
	v_mov_b64_e32 v[74:75], v[26:27]
	v_mov_b64_e32 v[72:73], v[24:25]
	v_mov_b64_e32 v[70:71], v[22:23]
	v_mov_b64_e32 v[68:69], v[20:21]
	v_mov_b64_e32 v[66:67], v[18:19]
	v_mov_b64_e32 v[64:65], v[16:17]
	v_mov_b64_e32 v[92:93], v[28:29]
	v_mov_b64_e32 v[90:91], v[26:27]
	v_mov_b64_e32 v[88:89], v[24:25]
	v_mov_b64_e32 v[86:87], v[22:23]
	v_mov_b64_e32 v[84:85], v[20:21]
	v_mov_b64_e32 v[82:83], v[18:19]
	v_mov_b64_e32 v[80:81], v[16:17]
	v_mov_b64_e32 v[108:109], v[28:29]
	v_mov_b64_e32 v[106:107], v[26:27]
	v_mov_b64_e32 v[104:105], v[24:25]
	v_mov_b64_e32 v[102:103], v[22:23]
	v_mov_b64_e32 v[100:101], v[20:21]
	v_mov_b64_e32 v[98:99], v[18:19]
	v_mov_b64_e32 v[96:97], v[16:17]
	s_mov_b32 s13, 0
	s_mov_b32 s0, 0
	s_and_saveexec_b64 s[62:63], s[6:7]
	s_cbranch_execz .Lgate_end_pre
; DI void mlstm_job(const PX& p, int l, int job, unsigned char* smem) {
;     ...
;       if (w == 0) {
;         const float gi = pgi + gbi;
;         const float gf = pgf + gbf;
;         const float lf = fminf(gf, 0.f) - log1pf(expf(-fabsf(gf)));
;         float bc = lf;
; #pragma unroll
;         for (int o = 1; o < 64; o <<= 1) { const float v = __shfl_up(bc, o); if (lane >= o) bc += v; }
	s_waitcnt vmcnt(0)
	v_add_f32_e32 v0, v174, v180
	s_mov_b32 s2, 0xbfb8aa3b
	v_mul_f32_e64 v2, |v0|, s2
	v_fma_f32 v3, |v0|, s2, -v2
	s_mov_b32 s1, 0xb2a5705f
	v_rndne_f32_e32 v4, v2
	v_fma_f32 v3, |v0|, s1, v3
	v_sub_f32_e32 v2, v2, v4
	v_add_f32_e32 v2, v2, v3
	v_exp_f32_e32 v2, v2
	v_cvt_i32_f32_e32 v3, v4
	s_mov_b32 s26, 0x42ce8ed0
	v_cmp_ngt_f32_e64 vcc, |v0|, s26
	s_mov_b32 s27, 0xc2b17218
	v_ldexp_f32 v2, v2, v3
	v_cndmask_b32_e32 v2, 0, v2, vcc
	v_cmp_nlt_f32_e64 vcc, |v0|, s27
	v_min_f32_e32 v4, 0, v0
	s_mov_b32 s1, 0x3f2aaaab
	v_cndmask_b32_e32 v0, v212, v2, vcc
	v_add_f32_e32 v5, 1.0, v0
	v_add_f32_e32 v2, -1.0, v5
	v_sub_f32_e32 v3, v2, v5
	v_add_f32_e32 v3, 1.0, v3
	v_sub_f32_e32 v2, v0, v2
	v_add_f32_e32 v6, v2, v3
	v_frexp_mant_f32_e32 v7, v5
	v_cvt_f64_f32_e32 v[2:3], v5
	v_frexp_exp_i32_f64_e32 v2, v[2:3]
	v_cmp_gt_f32_e32 vcc, s1, v7
	s_mov_b32 s1, 0x3f317218
	s_mov_b32 s3, 0xc2ce8ed0
	v_subbrev_co_u32_e32 v2, vcc, 0, v2, vcc
	v_sub_u32_e32 v3, 0, v2
	v_ldexp_f32 v5, v5, v3
	v_ldexp_f32 v3, v6, v3
	v_add_f32_e32 v6, -1.0, v5
	v_add_f32_e32 v9, 1.0, v5
	v_add_f32_e32 v7, 1.0, v6
	v_add_f32_e32 v10, -1.0, v9
	v_sub_f32_e32 v7, v5, v7
	v_sub_f32_e32 v5, v5, v10
	v_add_f32_e32 v7, v3, v7
	v_add_f32_e32 v3, v3, v5
	v_add_f32_e32 v5, v9, v3
	v_rcp_f32_e32 v10, v5
	v_add_f32_e32 v8, v6, v7
	v_sub_f32_e32 v6, v6, v8
	v_add_f32_e32 v6, v7, v6
	v_sub_f32_e32 v7, v9, v5
	v_add_f32_e32 v3, v3, v7
	v_mul_f32_e32 v7, v8, v10
	v_mul_f32_e32 v9, v5, v7
	v_fma_f32 v11, v7, v5, -v9
	v_fmac_f32_e32 v11, v7, v3
	v_add_f32_e32 v12, v9, v11
	v_sub_f32_e32 v13, v8, v12
	v_sub_f32_e32 v8, v8, v13
	v_sub_f32_e32 v9, v12, v9
	v_sub_f32_e32 v8, v8, v12
	v_add_f32_e32 v6, v6, v8
	v_sub_f32_e32 v8, v9, v11
	v_add_f32_e32 v6, v8, v6
	v_add_f32_e32 v8, v13, v6
	v_mul_f32_e32 v9, v10, v8
	v_mul_f32_e32 v11, v5, v9
	v_fma_f32 v5, v9, v5, -v11
	v_fmac_f32_e32 v5, v9, v3
	v_sub_f32_e32 v3, v13, v8
	v_add_f32_e32 v3, v6, v3
	v_add_f32_e32 v6, v11, v5
	v_sub_f32_e32 v12, v8, v6
	v_sub_f32_e32 v8, v8, v12
	v_sub_f32_e32 v11, v6, v11
	v_sub_f32_e32 v6, v8, v6
	v_add_f32_e32 v3, v3, v6
	v_sub_f32_e32 v5, v11, v5
	v_cvt_f32_i32_e32 v2, v2
	v_add_f32_e32 v3, v5, v3
	v_add_f32_e32 v5, v7, v9
	v_add_f32_e32 v3, v12, v3
	v_sub_f32_e32 v6, v5, v7
	v_mul_f32_e32 v3, v10, v3
	v_sub_f32_e32 v6, v9, v6
	v_add_f32_e32 v3, v6, v3
	v_mul_f32_e32 v9, 0x3f317218, v2
	v_add_f32_e32 v6, v5, v3
	v_fma_f32 v10, v2, s1, -v9
	v_mul_f32_e32 v7, v6, v6
	v_mov_b32_e32 v8, 0x3ecc95a3
	v_fmac_f32_e32 v10, 0xb102e308, v2
	v_sub_f32_e32 v2, v6, v5
	v_fmamk_f32 v8, v7, 0x3e9b6dac, v8
	v_sub_f32_e32 v2, v3, v2
	v_add_f32_e32 v3, v9, v10
	v_fmaak_f32 v8, v7, v8, 0x3f2aaada
	v_sub_f32_e32 v5, v3, v9
	v_ldexp_f32 v9, v6, 1
	v_mul_f32_e32 v6, v6, v7
	v_mul_f32_e32 v6, v6, v8
	v_add_f32_e32 v7, v9, v6
	v_sub_f32_e32 v8, v7, v9
	v_ldexp_f32 v2, v2, 1
	v_sub_f32_e32 v6, v6, v8
	v_add_f32_e32 v2, v2, v6
	v_add_f32_e32 v6, v7, v2
	v_sub_f32_e32 v7, v6, v7
	v_sub_f32_e32 v2, v2, v7
	v_add_f32_e32 v7, v3, v6
	v_sub_f32_e32 v8, v7, v3
	v_sub_f32_e32 v9, v7, v8
	v_sub_f32_e32 v5, v10, v5
	v_sub_f32_e32 v3, v3, v9
	v_sub_f32_e32 v6, v6, v8
	v_add_f32_e32 v3, v6, v3
	v_add_f32_e32 v6, v5, v2
	v_sub_f32_e32 v8, v6, v5
	v_sub_f32_e32 v9, v6, v8
	v_sub_f32_e32 v5, v5, v9
	v_sub_f32_e32 v2, v2, v8
	v_add_f32_e32 v3, v6, v3
	v_add_f32_e32 v2, v2, v5
	v_add_f32_e32 v5, v7, v3
	v_sub_f32_e32 v6, v5, v7
	v_sub_f32_e32 v3, v3, v6
	v_add_f32_e32 v2, v2, v3
	s_mov_b32 s1, 0x7f800000
	v_add_f32_e32 v2, v5, v2
	v_cmp_neq_f32_e32 vcc, s1, v0
	s_mov_b32 s1, 0x33800000
	v_lshlrev_b32_e32 v6, 2, v175
	v_cndmask_b32_e32 v2, v212, v2, vcc
	v_cmp_lt_f32_e64 vcc, |v0|, s1
	s_mov_b32 s1, 0x3fb8aa3b
	v_lshl_or_b32 v6, s0, 8, v6
	v_cndmask_b32_e32 v0, v2, v0, vcc
	v_sub_f32_e32 v0, v4, v0
	ds_bpermute_b32 v2, v190, v0
	v_add_u32_e32 v7, 0x1d600, v6
	s_waitcnt lgkmcnt(0)
	v_add_f32_e32 v2, v0, v2
	v_cndmask_b32_e64 v0, v2, v0, s[14:15]
	ds_bpermute_b32 v2, v191, v0
	s_waitcnt lgkmcnt(0)
; DI void mlstm_job(const PX& p, int l, int job, unsigned char* smem) {
;     ...
;         for (int o = 1; o < 64; o <<= 1) { const float v = __shfl_up(bc, o); if (lane >= o) bc += v; }
;         const float rr = gi - bc;
;         float M = rr;
; #pragma unroll
;         for (int o = 1; o < 64; o <<= 1) { const float v = __shfl_up(M, o); if (lane >= o) M = fmaxf(M, v); }
;         const float mu = fmaxf(m, M);
;         const float b63 = __shfl(bc, 63), mu63 = __shfl(mu, 63);
;         rA[par * 64 + lane] = rr;
;         muA[par * 64 + lane] = mu;
;         wkA[par * 64 + lane] = expf(rr - mu63);
;         winA[par * 64 + lane] = expf(m - mu);
;         emtA[par * 64 + lane] = expf(-(bc + mu));
;         if (lane == 0) { scA[par * 4] = expf(m - mu63); scA[par * 4 + 1] = b63 + mu63; }
;       }
	v_add_f32_e32 v2, v0, v2
	v_cndmask_b32_e64 v0, v2, v0, s[18:19]
	ds_bpermute_b32 v2, v192, v0
	s_waitcnt lgkmcnt(0)
	v_add_f32_e32 v2, v0, v2
	v_cndmask_b32_e64 v0, v2, v0, s[20:21]
	ds_bpermute_b32 v2, v193, v0
	s_waitcnt lgkmcnt(0)
	v_add_f32_e32 v2, v0, v2
	v_cndmask_b32_e64 v0, v2, v0, s[22:23]
	ds_bpermute_b32 v2, v194, v0
	s_waitcnt lgkmcnt(0)
	v_add_f32_e32 v2, v0, v2
	v_cndmask_b32_e64 v0, v2, v0, s[24:25]
	ds_bpermute_b32 v2, v195, v0
	s_waitcnt lgkmcnt(0)
	v_add_f32_e32 v2, v0, v2
	v_cndmask_b32_e64 v3, v2, v0, s[16:17]
	v_add_f32_e32 v0, v161, v177
	v_sub_f32_e32 v4, v0, v3
	ds_bpermute_b32 v0, v190, v4
	ds_write_b32 v7, v4
	s_waitcnt lgkmcnt(1)
	v_max_f32_e32 v0, v0, v0
	v_max_f32_e32 v0, v4, v0
	v_cndmask_b32_e64 v0, v0, v4, s[14:15]
	ds_bpermute_b32 v2, v191, v0
	s_waitcnt lgkmcnt(0)
	v_max_f32_e32 v2, v2, v2
	v_max_f32_e32 v2, v0, v2
	v_cndmask_b32_e64 v0, v2, v0, s[18:19]
	ds_bpermute_b32 v2, v192, v0
	s_waitcnt lgkmcnt(0)
	v_max_f32_e32 v2, v2, v2
	v_max_f32_e32 v2, v0, v2
	v_cndmask_b32_e64 v0, v2, v0, s[20:21]
	ds_bpermute_b32 v2, v193, v0
	s_waitcnt lgkmcnt(0)
	v_max_f32_e32 v2, v2, v2
	v_max_f32_e32 v2, v0, v2
	v_cndmask_b32_e64 v0, v2, v0, s[22:23]
	ds_bpermute_b32 v2, v194, v0
	s_waitcnt lgkmcnt(0)
	v_max_f32_e32 v2, v2, v2
	v_max_f32_e32 v2, v0, v2
	v_cndmask_b32_e64 v0, v2, v0, s[24:25]
	ds_bpermute_b32 v2, v195, v0
	v_max_f32_e32 v5, v0, v0
	s_waitcnt lgkmcnt(0)
	v_max_f32_e32 v2, v2, v2
	v_max_f32_e32 v2, v5, v2
	v_cndmask_b32_e64 v0, v2, v0, s[16:17]
	v_max_f32_e32 v0, v0, v0
	v_max_f32_e32 v2, v163, v163
	v_max_f32_e32 v5, v2, v0
	ds_bpermute_b32 v0, v183, v5
	v_sub_f32_e32 v7, v163, v5
	ds_bpermute_b32 v2, v183, v3
	v_add_f32_e32 v3, v3, v5
	s_waitcnt lgkmcnt(1)
	v_sub_f32_e32 v8, v4, v0
	v_mul_f32_e32 v9, 0x3fb8aa3b, v8
	v_fma_f32 v10, v8, s1, -v9
	v_rndne_f32_e32 v11, v9
	v_fmac_f32_e32 v10, 0x32a5705f, v8
	v_sub_f32_e32 v9, v9, v11
	v_add_f32_e32 v9, v9, v10
	v_exp_f32_e32 v9, v9
	v_cvt_i32_f32_e32 v10, v11
	v_add_u32_e32 v4, 0x1d800, v6
	ds_write_b32 v4, v5
	v_cmp_ngt_f32_e32 vcc, s3, v8
	v_ldexp_f32 v4, v9, v10
	v_mul_f32_e32 v9, 0x3fb8aa3b, v7
	v_fma_f32 v10, v7, s1, -v9
	v_rndne_f32_e32 v11, v9
	v_fmac_f32_e32 v10, 0x32a5705f, v7
	v_sub_f32_e32 v9, v9, v11
	v_add_f32_e32 v9, v9, v10
	v_exp_f32_e32 v9, v9
	v_cvt_i32_f32_e32 v10, v11
	s_mov_b32 s1, 0x42b17218
	v_cndmask_b32_e32 v4, 0, v4, vcc
	v_cmp_nlt_f32_e32 vcc, s1, v8
	v_add_u32_e32 v8, 0x1da00, v6
	v_mul_f32_e32 v5, 0xbfb8aa3b, v3
	v_cndmask_b32_e32 v4, v212, v4, vcc
	ds_write_b32 v8, v4
	v_ldexp_f32 v4, v9, v10
	v_fma_f32 v8, v3, s2, -v5
	v_rndne_f32_e32 v9, v5
	v_fmac_f32_e32 v8, 0xb2a5705f, v3
	v_sub_f32_e32 v5, v5, v9
	v_add_f32_e32 v5, v5, v8
	v_exp_f32_e32 v5, v5
	v_cvt_i32_f32_e32 v8, v9
	v_cmp_ngt_f32_e32 vcc, s3, v7
	s_nop 1
	v_cndmask_b32_e32 v4, 0, v4, vcc
	v_cmp_nlt_f32_e32 vcc, s1, v7
	v_add_u32_e32 v7, 0x1dc00, v6
	s_nop 0
	v_cndmask_b32_e32 v4, v212, v4, vcc
	ds_write_b32 v7, v4
	v_ldexp_f32 v4, v5, v8
	v_cmp_nlt_f32_e32 vcc, s26, v3
	s_nop 1
	v_cndmask_b32_e32 v4, 0, v4, vcc
	v_cmp_ngt_f32_e32 vcc, s27, v3
	s_nop 1
	v_cndmask_b32_e32 v3, v212, v4, vcc
	v_add_u32_e32 v4, 0x1de00, v6
	ds_write_b32 v4, v3
	s_and_b64 exec, exec, s[14:15]
	s_cbranch_execz .Lgate_end_pre
	v_sub_f32_e32 v4, v163, v0
	v_mul_f32_e32 v3, 0x3fb8aa3b, v4
	s_mov_b32 s1, 0x3fb8aa3b
	v_fma_f32 v5, v4, s1, -v3
	v_rndne_f32_e32 v6, v3
	v_fmac_f32_e32 v5, 0x32a5705f, v4
	v_sub_f32_e32 v3, v3, v6
	v_add_f32_e32 v3, v3, v5
	v_exp_f32_e32 v5, v3
	v_cvt_i32_f32_e32 v6, v6
	s_mov_b32 s2, 0xc2ce8ed0
	s_lshl_b32 s1, s0, 4
	s_waitcnt lgkmcnt(4)
	v_add_f32_e32 v3, v2, v0
	v_ldexp_f32 v0, v5, v6
	v_cmp_ngt_f32_e32 vcc, s2, v4
	s_mov_b32 s2, 0x42b17218
	s_or_b32 s1, s1, 0x1e000
	v_cndmask_b32_e32 v0, 0, v0, vcc
	v_cmp_nlt_f32_e32 vcc, s2, v4
	s_nop 1
	v_cndmask_b32_e32 v2, v212, v0, vcc
	v_mov_b32_e32 v0, s1
	ds_write_b64 v0, v[2:3]
.Lgate_end_pre:
	s_or_b64 exec, exec, s[62:63]
	s_waitcnt vmcnt(0)
	v_lshl_add_u32 v208, v211, 4, s82
	v_add_u32_e32 v208, 0x21100, v208
	s_branch .LBB0_449

; DI void mlstm_job(const PX& p, int l, int job, unsigned char* smem) {
;     ...
;       if (w == 0 && cc + 1 < 36) {
;         const int sg = (cc + 1) >= 4;
;         const int pos = (sg ? cc + 1 - 4 : cc + 1) * 64 + lane;
;         const int Ls = sg ? 2048 : 256;
;         const int t = dir ? Ls - 1 - pos : pos;
;         const int tok = (sg ? b * 2048 : NLAT + b * 256) + t;
;         pgi = Zgt[(size_t)tok * 16 + (dir ? 8 : 0) + h];
;         pgf = Zgt[(size_t)tok * 16 + (dir ? 12 : 4) + h];
;       }
.LBB0_452:
	s_or_b64 exec, exec, s[62:63]
	s_cmp_lg_u32 s13, 35
	s_cselect_b64 s[2:3], -1, 0
	s_and_b64 s[2:3], s[76:77], s[2:3]
	s_waitcnt lgkmcnt(0)
	s_barrier
	s_waitcnt vmcnt(0)
	s_and_saveexec_b64 s[62:63], s[2:3]
	s_cbranch_execz .LBB0_454
	s_cmp_gt_u32 s13, 2
	s_cselect_b32 s1, -3, 1
	s_movk_i32 s2, 0x7ff
	s_cselect_b32 s2, s2, 0xff
	s_cselect_b32 s3, s11, s12
	s_add_i32 s1, s1, s13
	v_lshl_or_b32 v0, s1, 6, v175
	v_sub_u32_e32 v2, s2, v0
	v_cndmask_b32_e64 v0, v2, v0, s[4:5]
	v_add_u32_e32 v2, s3, v0
	v_ashrrev_i32_e32 v3, 31, v2
	v_readlane_b32 s2, v254, 14
	v_lshlrev_b64 v[2:3], 6, v[2:3]
	v_readlane_b32 s3, v254, 15
	s_nop 1
	v_lshl_add_u64 v[2:3], s[2:3], 0, v[2:3]
	v_readlane_b32 s2, v253, 31
	v_readlane_b32 s3, v253, 32
	s_mov_b32 s61, s3
	s_mov_b32 s69, s3
	v_lshl_add_u64 v[4:5], v[2:3], 0, s[2:3]
	v_lshl_add_u64 v[4:5], v[4:5], 0, s[60:61]
	v_lshl_add_u64 v[2:3], v[2:3], 0, s[68:69]
	v_lshl_add_u64 v[2:3], v[2:3], 0, s[60:61]
	global_load_dword v177, v[4:5], off
	global_load_dword v180, v[2:3], off

; DI void mlstm_job(const PX& p, int l, int job, unsigned char* smem) {
;     ...
;       const int par = cc & 1;
;       if (w == 0) {
;         const float gi = pgi + gbi;
;         const float gf = pgf + gbf;
;         const float lf = fminf(gf, 0.f) - log1pf(expf(-fabsf(gf)));
;         float bc = lf;
; #pragma unroll
;         for (int o = 1; o < 64; o <<= 1) { const float v = __shfl_up(bc, o); if (lane >= o) bc += v; }
;         const float rr = gi - bc;
;         float M = rr;
; #pragma unroll
;         for (int o = 1; o < 64; o <<= 1) { const float v = __shfl_up(M, o); if (lane >= o) M = fmaxf(M, v); }
;         const float mu = fmaxf(m, M);
;         const float b63 = __shfl(bc, 63), mu63 = __shfl(mu, 63);
;         rA[par * 64 + lane] = rr;
;         muA[par * 64 + lane] = mu;
;         wkA[par * 64 + lane] = expf(rr - mu63);
;         winA[par * 64 + lane] = expf(m - mu);
;         emtA[par * 64 + lane] = expf(-(bc + mu));
;         if (lane == 0) { scA[par * 4] = expf(m - mu63); scA[par * 4 + 1] = b63 + mu63; }
.LBB0_458:
	s_or_b64 exec, exec, s[62:63]
	s_cmp_eq_u32 s13, 35
	s_cbranch_scc1 .Lgate_skip
	s_add_i32 s0, s13, 1
	s_and_b32 s0, s0, 1
	s_and_saveexec_b64 s[62:63], s[6:7]
	s_cbranch_execz .Lgate_end_loop
	s_waitcnt vmcnt(0)
	v_add_f32_e32 v0, v174, v180
	s_mov_b32 s2, 0xbfb8aa3b
	v_mul_f32_e64 v2, |v0|, s2
	v_fma_f32 v3, |v0|, s2, -v2
	s_mov_b32 s1, 0xb2a5705f
	v_rndne_f32_e32 v4, v2
	v_fma_f32 v3, |v0|, s1, v3
	v_sub_f32_e32 v2, v2, v4
	v_add_f32_e32 v2, v2, v3
	v_exp_f32_e32 v2, v2
	v_cvt_i32_f32_e32 v3, v4
	s_mov_b32 s26, 0x42ce8ed0
	v_cmp_ngt_f32_e64 vcc, |v0|, s26
	s_mov_b32 s27, 0xc2b17218
	v_ldexp_f32 v2, v2, v3
	v_cndmask_b32_e32 v2, 0, v2, vcc
	v_cmp_nlt_f32_e64 vcc, |v0|, s27
	v_min_f32_e32 v4, 0, v0
	s_mov_b32 s1, 0x3f2aaaab
	v_cndmask_b32_e32 v0, v212, v2, vcc
	v_add_f32_e32 v5, 1.0, v0
	v_add_f32_e32 v2, -1.0, v5
	v_sub_f32_e32 v3, v2, v5
	v_add_f32_e32 v3, 1.0, v3
	v_sub_f32_e32 v2, v0, v2
	v_add_f32_e32 v6, v2, v3
	v_frexp_mant_f32_e32 v7, v5
	v_cvt_f64_f32_e32 v[2:3], v5
	v_frexp_exp_i32_f64_e32 v2, v[2:3]
	v_cmp_gt_f32_e32 vcc, s1, v7
	s_mov_b32 s1, 0x3f317218
	s_mov_b32 s3, 0xc2ce8ed0
	v_subbrev_co_u32_e32 v2, vcc, 0, v2, vcc
	v_sub_u32_e32 v3, 0, v2
	v_ldexp_f32 v5, v5, v3
	v_ldexp_f32 v3, v6, v3
	v_add_f32_e32 v6, -1.0, v5
	v_add_f32_e32 v9, 1.0, v5
	v_add_f32_e32 v7, 1.0, v6
	v_add_f32_e32 v10, -1.0, v9
	v_sub_f32_e32 v7, v5, v7
	v_sub_f32_e32 v5, v5, v10
	v_add_f32_e32 v7, v3, v7
	v_add_f32_e32 v3, v3, v5
	v_add_f32_e32 v5, v9, v3
	v_rcp_f32_e32 v10, v5
	v_add_f32_e32 v8, v6, v7
	v_sub_f32_e32 v6, v6, v8
	v_add_f32_e32 v6, v7, v6
	v_sub_f32_e32 v7, v9, v5
	v_add_f32_e32 v3, v3, v7
	v_mul_f32_e32 v7, v8, v10
	v_mul_f32_e32 v9, v5, v7
	v_fma_f32 v11, v7, v5, -v9
	v_fmac_f32_e32 v11, v7, v3
	v_add_f32_e32 v12, v9, v11
	v_sub_f32_e32 v13, v8, v12
	v_sub_f32_e32 v8, v8, v13
	v_sub_f32_e32 v9, v12, v9
	v_sub_f32_e32 v8, v8, v12
	v_add_f32_e32 v6, v6, v8
	v_sub_f32_e32 v8, v9, v11
	v_add_f32_e32 v6, v8, v6
	v_add_f32_e32 v8, v13, v6
	v_mul_f32_e32 v9, v10, v8
	v_mul_f32_e32 v11, v5, v9
	v_fma_f32 v5, v9, v5, -v11
	v_fmac_f32_e32 v5, v9, v3
	v_sub_f32_e32 v3, v13, v8
	v_add_f32_e32 v3, v6, v3
	v_add_f32_e32 v6, v11, v5
	v_sub_f32_e32 v12, v8, v6
	v_sub_f32_e32 v8, v8, v12
	v_sub_f32_e32 v11, v6, v11
	v_sub_f32_e32 v6, v8, v6
	v_add_f32_e32 v3, v3, v6
	v_sub_f32_e32 v5, v11, v5
	v_cvt_f32_i32_e32 v2, v2
	v_add_f32_e32 v3, v5, v3
	v_add_f32_e32 v5, v7, v9
	v_add_f32_e32 v3, v12, v3
	v_sub_f32_e32 v6, v5, v7
	v_mul_f32_e32 v3, v10, v3
	v_sub_f32_e32 v6, v9, v6
	v_add_f32_e32 v3, v6, v3
	v_mul_f32_e32 v9, 0x3f317218, v2
	v_add_f32_e32 v6, v5, v3
	v_fma_f32 v10, v2, s1, -v9
	v_mul_f32_e32 v7, v6, v6
	v_mov_b32_e32 v8, 0x3ecc95a3
	v_fmac_f32_e32 v10, 0xb102e308, v2
	v_sub_f32_e32 v2, v6, v5
	v_fmamk_f32 v8, v7, 0x3e9b6dac, v8
	v_sub_f32_e32 v2, v3, v2
	v_add_f32_e32 v3, v9, v10
	v_fmaak_f32 v8, v7, v8, 0x3f2aaada
	v_sub_f32_e32 v5, v3, v9
	v_ldexp_f32 v9, v6, 1
	v_mul_f32_e32 v6, v6, v7
	v_mul_f32_e32 v6, v6, v8
	v_add_f32_e32 v7, v9, v6
	v_sub_f32_e32 v8, v7, v9
	v_ldexp_f32 v2, v2, 1
	v_sub_f32_e32 v6, v6, v8
	v_add_f32_e32 v2, v2, v6
	v_add_f32_e32 v6, v7, v2
	v_sub_f32_e32 v7, v6, v7
	v_sub_f32_e32 v2, v2, v7
	v_add_f32_e32 v7, v3, v6
	v_sub_f32_e32 v8, v7, v3
	v_sub_f32_e32 v9, v7, v8
	v_sub_f32_e32 v5, v10, v5
	v_sub_f32_e32 v3, v3, v9
	v_sub_f32_e32 v6, v6, v8
	v_add_f32_e32 v3, v6, v3
	v_add_f32_e32 v6, v5, v2
	v_sub_f32_e32 v8, v6, v5
	v_sub_f32_e32 v9, v6, v8
	v_sub_f32_e32 v5, v5, v9
	v_sub_f32_e32 v2, v2, v8
	v_add_f32_e32 v3, v6, v3
	v_add_f32_e32 v2, v2, v5
	v_add_f32_e32 v5, v7, v3
	v_sub_f32_e32 v6, v5, v7
	v_sub_f32_e32 v3, v3, v6
	v_add_f32_e32 v2, v2, v3
	s_mov_b32 s1, 0x7f800000
	v_add_f32_e32 v2, v5, v2
	v_cmp_neq_f32_e32 vcc, s1, v0
	s_mov_b32 s1, 0x33800000
	v_lshlrev_b32_e32 v6, 2, v175
	v_cndmask_b32_e32 v2, v212, v2, vcc
	v_cmp_lt_f32_e64 vcc, |v0|, s1
	s_mov_b32 s1, 0x3fb8aa3b
	v_lshl_or_b32 v6, s0, 8, v6
	v_cndmask_b32_e32 v0, v2, v0, vcc
	v_sub_f32_e32 v0, v4, v0
	ds_bpermute_b32 v2, v190, v0
	v_add_u32_e32 v7, 0x1d600, v6
	s_waitcnt lgkmcnt(0)
	v_add_f32_e32 v2, v0, v2
	v_cndmask_b32_e64 v0, v2, v0, s[14:15]
	ds_bpermute_b32 v2, v191, v0
	s_waitcnt lgkmcnt(0)
	v_add_f32_e32 v2, v0, v2
	v_cndmask_b32_e64 v0, v2, v0, s[18:19]
	ds_bpermute_b32 v2, v192, v0
	s_waitcnt lgkmcnt(0)
	v_add_f32_e32 v2, v0, v2
	v_cndmask_b32_e64 v0, v2, v0, s[20:21]
	ds_bpermute_b32 v2, v193, v0
	s_waitcnt lgkmcnt(0)
	v_add_f32_e32 v2, v0, v2
	v_cndmask_b32_e64 v0, v2, v0, s[22:23]
	ds_bpermute_b32 v2, v194, v0
	s_waitcnt lgkmcnt(0)
	v_add_f32_e32 v2, v0, v2
	v_cndmask_b32_e64 v0, v2, v0, s[24:25]
	ds_bpermute_b32 v2, v195, v0
	s_waitcnt lgkmcnt(0)
	v_add_f32_e32 v2, v0, v2
	v_cndmask_b32_e64 v3, v2, v0, s[16:17]
	v_add_f32_e32 v0, v161, v177
	v_sub_f32_e32 v4, v0, v3
	ds_bpermute_b32 v0, v190, v4
	ds_write_b32 v7, v4
	s_waitcnt lgkmcnt(1)
; DI unsigned pack2(float a, float b) { f32x2_t v = {a, b}; bf16x2_t r = __builtin_convertvector(v, bf16x2_t); return __builtin_bit_cast(unsigned, r); }
; DI f32x16 mfma32(bf16x8 a, bf16x8 b, f32x16 c) { return __builtin_amdgcn_mfma_f32_32x32x16_bf16(a, b, c, 0, 0, 0); }
; DI void mlstm_job(const PX& p, int l, int job, unsigned char* smem) {
;     ...
;         for (int o = 1; o < 64; o <<= 1) { const float v = __shfl_up(bc, o); if (lane >= o) bc += v; }
;         const float rr = gi - bc;
;         float M = rr;
; #pragma unroll
;         for (int o = 1; o < 64; o <<= 1) { const float v = __shfl_up(M, o); if (lane >= o) M = fmaxf(M, v); }
;         const float mu = fmaxf(m, M);
;         const float b63 = __shfl(bc, 63), mu63 = __shfl(mu, 63);
;         rA[par * 64 + lane] = rr;
;         muA[par * 64 + lane] = mu;
;         wkA[par * 64 + lane] = expf(rr - mu63);
;         winA[par * 64 + lane] = expf(m - mu);
;         emtA[par * 64 + lane] = expf(-(bc + mu));
;         if (lane == 0) { scA[par * 4] = expf(m - mu63); scA[par * 4 + 1] = b63 + mu63; }
;       }
;     ...
;       if (w < 7) {
; #pragma unroll
;         for (int i = 0; i < 6; i++) {
; #pragma unroll
;           for (int s2 = 0; s2 < 2; s2++) {
;             uint4 pk;
;             pk.x = pack2(st[i][8 * s2 + 0], st[i][8 * s2 + 1]);
;             pk.y = pack2(st[i][8 * s2 + 2], st[i][8 * s2 + 3]);
;             pk.z = pack2(st[i][8 * s2 + 4], st[i][8 * s2 + 5]);
;             pk.w = pack2(st[i][8 * s2 + 6], st[i][8 * s2 + 7]);
;             const bf16x8 aop = u4_to_bf8(pk);
; #pragma unroll
;             for (int ti = 0; ti < 2; ti++) {
;               const bfu* qp = sq + (ti * 32 + lr) * 200 + 32 * i + 16 * s2 + 4 * lh;
;               const uint2 lo = *(const uint2*)qp;
;               const uint2 hi = *(const uint2*)(qp + 8);
;               const uint4 bq = make_uint4(lo.x, lo.y, hi.x, hi.y);
;               num[ti] = mfma32(aop, u4_to_bf8(bq), num[ti]);
	v_max_f32_e32 v0, v0, v0
	v_max_f32_e32 v0, v4, v0
	v_cndmask_b32_e64 v0, v0, v4, s[14:15]
	ds_bpermute_b32 v2, v191, v0
	s_waitcnt lgkmcnt(0)
	v_max_f32_e32 v2, v2, v2
	v_max_f32_e32 v2, v0, v2
	v_cndmask_b32_e64 v0, v2, v0, s[18:19]
	ds_bpermute_b32 v2, v192, v0
	s_waitcnt lgkmcnt(0)
	v_max_f32_e32 v2, v2, v2
	v_max_f32_e32 v2, v0, v2
	v_cndmask_b32_e64 v0, v2, v0, s[20:21]
	ds_bpermute_b32 v2, v193, v0
	s_waitcnt lgkmcnt(0)
	v_max_f32_e32 v2, v2, v2
	v_max_f32_e32 v2, v0, v2
	v_cndmask_b32_e64 v0, v2, v0, s[22:23]
	ds_bpermute_b32 v2, v194, v0
	s_waitcnt lgkmcnt(0)
	v_max_f32_e32 v2, v2, v2
	v_max_f32_e32 v2, v0, v2
	v_cndmask_b32_e64 v0, v2, v0, s[24:25]
	ds_bpermute_b32 v2, v195, v0
	v_max_f32_e32 v5, v0, v0
	s_waitcnt lgkmcnt(0)
	v_max_f32_e32 v2, v2, v2
	v_max_f32_e32 v2, v5, v2
	v_cndmask_b32_e64 v0, v2, v0, s[16:17]
	v_max_f32_e32 v0, v0, v0
	v_max_f32_e32 v2, v163, v163
	v_max_f32_e32 v5, v2, v0
	ds_bpermute_b32 v0, v183, v5
	v_sub_f32_e32 v7, v163, v5
	ds_bpermute_b32 v2, v183, v3
	v_add_f32_e32 v3, v3, v5
	s_waitcnt lgkmcnt(1)
	v_sub_f32_e32 v8, v4, v0
	v_mul_f32_e32 v9, 0x3fb8aa3b, v8
	v_fma_f32 v10, v8, s1, -v9
	v_rndne_f32_e32 v11, v9
	v_fmac_f32_e32 v10, 0x32a5705f, v8
	v_sub_f32_e32 v9, v9, v11
	v_add_f32_e32 v9, v9, v10
	v_exp_f32_e32 v9, v9
	v_cvt_i32_f32_e32 v10, v11
	v_add_u32_e32 v4, 0x1d800, v6
	ds_write_b32 v4, v5
	v_cmp_ngt_f32_e32 vcc, s3, v8
	v_ldexp_f32 v4, v9, v10
	v_mul_f32_e32 v9, 0x3fb8aa3b, v7
	v_fma_f32 v10, v7, s1, -v9
	v_rndne_f32_e32 v11, v9
	v_fmac_f32_e32 v10, 0x32a5705f, v7
	v_sub_f32_e32 v9, v9, v11
	v_add_f32_e32 v9, v9, v10
	v_exp_f32_e32 v9, v9
	v_cvt_i32_f32_e32 v10, v11
	s_mov_b32 s1, 0x42b17218
	v_cndmask_b32_e32 v4, 0, v4, vcc
	v_cmp_nlt_f32_e32 vcc, s1, v8
	v_add_u32_e32 v8, 0x1da00, v6
	v_mul_f32_e32 v5, 0xbfb8aa3b, v3
	v_cndmask_b32_e32 v4, v212, v4, vcc
	ds_write_b32 v8, v4
	v_ldexp_f32 v4, v9, v10
	v_fma_f32 v8, v3, s2, -v5
	v_rndne_f32_e32 v9, v5
	v_fmac_f32_e32 v8, 0xb2a5705f, v3
	v_sub_f32_e32 v5, v5, v9
	v_add_f32_e32 v5, v5, v8
	v_exp_f32_e32 v5, v5
	v_cvt_i32_f32_e32 v8, v9
	v_cmp_ngt_f32_e32 vcc, s3, v7
	s_nop 1
	v_cndmask_b32_e32 v4, 0, v4, vcc
	v_cmp_nlt_f32_e32 vcc, s1, v7
	v_add_u32_e32 v7, 0x1dc00, v6
	s_nop 0
	v_cndmask_b32_e32 v4, v212, v4, vcc
	ds_write_b32 v7, v4
	v_ldexp_f32 v4, v5, v8
	v_cmp_nlt_f32_e32 vcc, s26, v3
	s_nop 1
	v_cndmask_b32_e32 v4, 0, v4, vcc
	v_cmp_ngt_f32_e32 vcc, s27, v3
	s_nop 1
	v_cndmask_b32_e32 v3, v212, v4, vcc
	v_add_u32_e32 v4, 0x1de00, v6
	ds_write_b32 v4, v3
	s_and_b64 exec, exec, s[14:15]
	s_cbranch_execz .Lgate_end_loop
	v_sub_f32_e32 v4, v163, v0
	v_mul_f32_e32 v3, 0x3fb8aa3b, v4
	s_mov_b32 s1, 0x3fb8aa3b
	v_fma_f32 v5, v4, s1, -v3
	v_rndne_f32_e32 v6, v3
	v_fmac_f32_e32 v5, 0x32a5705f, v4
	v_sub_f32_e32 v3, v3, v6
	v_add_f32_e32 v3, v3, v5
	v_exp_f32_e32 v5, v3
	v_cvt_i32_f32_e32 v6, v6
	s_mov_b32 s2, 0xc2ce8ed0
	s_lshl_b32 s1, s0, 4
	s_waitcnt lgkmcnt(4)
	v_add_f32_e32 v3, v2, v0
	v_ldexp_f32 v0, v5, v6
	v_cmp_ngt_f32_e32 vcc, s2, v4
	s_mov_b32 s2, 0x42b17218
	s_or_b32 s1, s1, 0x1e000
	v_cndmask_b32_e32 v0, 0, v0, vcc
	v_cmp_nlt_f32_e32 vcc, s2, v4
	s_nop 1
	v_cndmask_b32_e32 v2, v212, v0, vcc
	v_mov_b32_e32 v0, s1
	ds_write_b64 v0, v[2:3]
.Lgate_end_loop:
	s_or_b64 exec, exec, s[62:63]
	s_and_b32 s0, s13, 1
.Lgate_skip:
	s_waitcnt lgkmcnt(0)
	s_barrier
	s_and_saveexec_b64 s[62:63], s[8:9]
	s_cbranch_execz .LBB0_462
	ds_read_b128 v[6:9], v187
	ds_read_b128 v[2:5], v187 offset:32
	ds_read_b128 v[10:13], v216
	ds_read_b128 v[144:147], v216 offset:32
	s_waitcnt lgkmcnt(1)
	v_mfma_f32_32x32x16_bf16 v[128:143], v[6:9], v[10:13], v[128:143]
	s_waitcnt lgkmcnt(0)
	v_mfma_f32_32x32x16_bf16 v[128:143], v[2:5], v[144:147], v[128:143]
	ds_read_b128 v[10:13], v187 offset:64
	ds_read_b128 v[144:147], v216 offset:64
	s_waitcnt lgkmcnt(0)
	v_mfma_f32_32x32x16_bf16 v[128:143], v[10:13], v[144:147], v[128:143]
	ds_read_b128 v[144:147], v187 offset:96
	ds_read_b128 v[148:151], v216 offset:96
	s_waitcnt lgkmcnt(0)
	v_mfma_f32_32x32x16_bf16 v[128:143], v[144:147], v[148:151], v[128:143]
	ds_read_b128 v[148:151], v216 offset:4608
	s_waitcnt lgkmcnt(0)
	v_mfma_f32_32x32x16_bf16 v[112:127], v[6:9], v[148:151], v[112:127]
	ds_read_b128 v[148:151], v216 offset:4640
	s_waitcnt lgkmcnt(0)
	v_mfma_f32_32x32x16_bf16 v[112:127], v[2:5], v[148:151], v[112:127]
	ds_read_b128 v[148:151], v216 offset:4672
	s_waitcnt lgkmcnt(0)
	v_mfma_f32_32x32x16_bf16 v[112:127], v[10:13], v[148:151], v[112:127]
	ds_read_b128 v[148:151], v216 offset:4704
	s_waitcnt lgkmcnt(0)
	v_mfma_f32_32x32x16_bf16 v[112:127], v[144:147], v[148:151], v[112:127]
	s_and_saveexec_b64 vcc, s[36:37]
	s_cbranch_execz .LBB0_461
	s_nop 9
	ds_write2_b32 v189, v128, v112 offset1:32
	ds_read_b128 v[6:9], v187
	ds_read_b128 v[2:5], v187 offset:32
	ds_read_b128 v[10:13], v187 offset:64
	ds_read_b128 v[144:147], v187 offset:96
